# v10: v9 + nt (streaming) policy on P6b's int8 act row stores
# speedup vs baseline: 1.0054x; 1.0015x over previous
.LBB0_909:
	s_waitcnt lgkmcnt(0)
	v_lshl_add_u64 v[4:5], s[8:9], 0, v[2:3]
	v_add_co_u32_e32 v24, vcc, 0x23000000, v4
	s_nop 1
	v_addc_co_u32_e32 v25, vcc, 0, v5, vcc
	global_load_dwordx2 v[86:87], v[24:25], off nt
	v_add_co_u32_e32 v54, vcc, s24, v4
	s_nop 1
	v_addc_co_u32_e32 v55, vcc, 0, v5, vcc
	v_add_co_u32_e32 v88, vcc, s25, v4
	s_nop 1
	v_addc_co_u32_e32 v89, vcc, 0, v5, vcc
	v_add_co_u32_e32 v90, vcc, s26, v4
	s_nop 1
	v_addc_co_u32_e32 v91, vcc, 0, v5, vcc
	global_load_dwordx2 v[36:37], v[54:55], off offset:1024 nt
	global_load_dwordx2 v[34:35], v[54:55], off offset:1536 nt
	global_load_dwordx2 v[32:33], v[54:55], off offset:2048 nt
	global_load_dwordx2 v[30:31], v[54:55], off offset:2560 nt
	global_load_dwordx2 v[22:23], v[88:89], off offset:512 nt
	global_load_dwordx2 v[20:21], v[88:89], off offset:1024 nt
	global_load_dwordx2 v[18:19], v[88:89], off offset:1536 nt
	global_load_dwordx2 v[16:17], v[88:89], off offset:2048 nt
	global_load_dwordx2 v[14:15], v[88:89], off offset:2560 nt
	global_load_dwordx2 v[12:13], v[88:89], off offset:3072 nt
	global_load_dwordx2 v[10:11], v[88:89], off offset:3584 nt
	global_load_dwordx2 v[28:29], v[54:55], off offset:3072 nt
	global_load_dwordx2 v[26:27], v[54:55], off offset:3584 nt
	global_load_dwordx2 v[8:9], v[90:91], off nt
	global_load_dwordx2 v[6:7], v[90:91], off offset:512 nt
	global_load_dwordx2 v[92:93], v[24:25], off offset:512 nt
	global_load_dwordx2 v[94:95], v[24:25], off offset:1024 nt
	global_load_dwordx2 v[96:97], v[24:25], off offset:1536 nt
	global_load_dwordx2 v[80:81], v[24:25], off offset:2048 nt
	global_load_dwordx2 v[78:79], v[24:25], off offset:2560 nt
	global_load_dwordx2 v[76:77], v[24:25], off offset:3072 nt
	global_load_dwordx2 v[74:75], v[24:25], off offset:3584 nt
	v_add_co_u32_e32 v56, vcc, s22, v4
	s_nop 1
	v_addc_co_u32_e32 v57, vcc, 0, v5, vcc
	v_add_co_u32_e32 v98, vcc, s23, v4
	s_nop 1
	v_addc_co_u32_e32 v99, vcc, 0, v5, vcc
	global_load_dwordx2 v[70:71], v[56:57], off offset:512 nt
	global_load_dwordx2 v[68:69], v[56:57], off offset:1024 nt
	global_load_dwordx2 v[66:67], v[56:57], off offset:1536 nt
	global_load_dwordx2 v[64:65], v[56:57], off offset:2048 nt
	global_load_dwordx2 v[62:63], v[56:57], off offset:2560 nt
	global_load_dwordx2 v[60:61], v[56:57], off offset:3072 nt
	global_load_dwordx2 v[58:59], v[56:57], off offset:3584 nt
	global_load_dwordx2 v[38:39], v[54:55], off offset:512 nt
	global_load_dwordx2 v[52:53], v[98:99], off offset:1024 nt
	global_load_dwordx2 v[50:51], v[98:99], off offset:1536 nt
	global_load_dwordx2 v[48:49], v[98:99], off offset:2048 nt
	global_load_dwordx2 v[46:47], v[98:99], off offset:2560 nt
	global_load_dwordx2 v[44:45], v[98:99], off offset:3072 nt
	global_load_dwordx2 v[42:43], v[98:99], off offset:3584 nt
	global_load_dwordx2 v[40:41], v[88:89], off offset:-4096 nt
	global_load_dwordx2 v[24:25], v[88:89], off nt
	global_load_dwordx2 v[72:73], v[98:99], off offset:-4096 nt
	global_load_dwordx2 v[56:57], v[98:99], off nt
	global_load_dwordx2 v[54:55], v[98:99], off offset:512 nt
	global_load_dwordx2 v[4:5], v[90:91], off offset:1024 nt
	s_waitcnt vmcnt(42)
	v_lshlrev_b32_e32 v88, 16, v86
	v_and_b32_e32 v86, 0xffff0000, v86
	v_lshlrev_b32_e32 v89, 16, v87
	v_and_b32_e32 v87, 0xffff0000, v87
	v_add_f32_e32 v90, v88, v86
	v_sub_f32_e32 v86, v88, v86
	v_add_f32_e32 v88, v89, v87
	v_sub_f32_e32 v87, v89, v87
	v_add_f32_e32 v89, v90, v88
	v_add_f32_e32 v91, v86, v87
	v_sub_f32_e32 v88, v90, v88
	v_sub_f32_e32 v86, v86, v87
	v_xor_b32_e32 v87, v82, v89
	v_xor_b32_e32 v90, v82, v91
	v_xor_b32_e32 v98, v82, v88
	v_add_f32_dpp v87, v89, v87 quad_perm:[1,0,3,2] row_mask:0xf bank_mask:0xf bound_ctrl:1
	v_add_f32_dpp v89, v91, v90 quad_perm:[1,0,3,2] row_mask:0xf bank_mask:0xf bound_ctrl:1
	v_xor_b32_e32 v90, v82, v86
	v_add_f32_dpp v88, v88, v98 quad_perm:[1,0,3,2] row_mask:0xf bank_mask:0xf bound_ctrl:1
	s_nop 0
	v_add_f32_dpp v86, v86, v90 quad_perm:[1,0,3,2] row_mask:0xf bank_mask:0xf bound_ctrl:1
	v_xor_b32_e32 v200, v83, v87
	v_xor_b32_e32 v201, v83, v89
	v_xor_b32_e32 v202, v83, v88
	v_xor_b32_e32 v203, v83, v86
	v_add_f32_dpp v204, v87, v200 quad_perm:[2,3,0,1] row_mask:0xf bank_mask:0xf bound_ctrl:1
	v_add_f32_dpp v205, v89, v201 quad_perm:[2,3,0,1] row_mask:0xf bank_mask:0xf bound_ctrl:1
	v_add_f32_dpp v206, v88, v202 quad_perm:[2,3,0,1] row_mask:0xf bank_mask:0xf bound_ctrl:1
	v_add_f32_dpp v207, v86, v203 quad_perm:[2,3,0,1] row_mask:0xf bank_mask:0xf bound_ctrl:1
	v_xor_b32_e32 v200, v84, v204
	v_xor_b32_e32 v201, v84, v205
	v_xor_b32_e32 v202, v84, v206
	v_xor_b32_e32 v203, v84, v207
	v_add_f32_dpp v87, v204, v200 row_shl:4 row_mask:0xf bank_mask:0x5
	v_add_f32_dpp v89, v205, v201 row_shl:4 row_mask:0xf bank_mask:0x5
	v_add_f32_dpp v88, v206, v202 row_shl:4 row_mask:0xf bank_mask:0x5
	v_add_f32_dpp v90, v207, v203 row_shl:4 row_mask:0xf bank_mask:0x5
	v_add_f32_dpp v87, v204, v200 row_shr:4 row_mask:0xf bank_mask:0xa
	v_add_f32_dpp v89, v205, v201 row_shr:4 row_mask:0xf bank_mask:0xa
	v_add_f32_dpp v88, v206, v202 row_shr:4 row_mask:0xf bank_mask:0xa
	v_add_f32_dpp v90, v207, v203 row_shr:4 row_mask:0xf bank_mask:0xa
	v_max_f32_e64 v86, |v87|, |v89|
	v_max_f32_e64 v91, |v88|, |v90|
	v_max3_f32 v91, v86, 0, v91
	v_cvt_pk_bf16_f32 v86, v87, v89
	v_cvt_pk_bf16_f32 v87, v88, v90
	s_waitcnt vmcnt(26)
	v_lshlrev_b32_e32 v88, 16, v92
	v_and_b32_e32 v89, 0xffff0000, v92
	v_lshlrev_b32_e32 v90, 16, v93
	v_and_b32_e32 v92, 0xffff0000, v93
	v_add_f32_e32 v93, v88, v89
	v_sub_f32_e32 v88, v88, v89
	v_add_f32_e32 v89, v90, v92
	v_sub_f32_e32 v90, v90, v92
	v_add_f32_e32 v92, v93, v89
	v_sub_f32_e32 v89, v93, v89
	v_add_f32_e32 v98, v88, v90
	v_sub_f32_e32 v88, v88, v90
	v_xor_b32_e32 v90, v82, v92
	v_xor_b32_e32 v93, v82, v89
	s_nop 0
	v_add_f32_dpp v90, v92, v90 quad_perm:[1,0,3,2] row_mask:0xf bank_mask:0xf bound_ctrl:1
	v_xor_b32_e32 v92, v82, v98
	v_add_f32_dpp v89, v89, v93 quad_perm:[1,0,3,2] row_mask:0xf bank_mask:0xf bound_ctrl:1
	v_xor_b32_e32 v93, v82, v88
	v_add_f32_dpp v92, v98, v92 quad_perm:[1,0,3,2] row_mask:0xf bank_mask:0xf bound_ctrl:1
	s_nop 0
	v_add_f32_dpp v88, v88, v93 quad_perm:[1,0,3,2] row_mask:0xf bank_mask:0xf bound_ctrl:1
	v_xor_b32_e32 v200, v83, v90
	v_xor_b32_e32 v201, v83, v92
	v_xor_b32_e32 v202, v83, v89
	v_xor_b32_e32 v203, v83, v88
	v_add_f32_dpp v204, v90, v200 quad_perm:[2,3,0,1] row_mask:0xf bank_mask:0xf bound_ctrl:1
	v_add_f32_dpp v205, v92, v201 quad_perm:[2,3,0,1] row_mask:0xf bank_mask:0xf bound_ctrl:1
	v_add_f32_dpp v206, v89, v202 quad_perm:[2,3,0,1] row_mask:0xf bank_mask:0xf bound_ctrl:1
	v_add_f32_dpp v207, v88, v203 quad_perm:[2,3,0,1] row_mask:0xf bank_mask:0xf bound_ctrl:1
	v_xor_b32_e32 v200, v84, v204
	v_xor_b32_e32 v201, v84, v205
	v_xor_b32_e32 v202, v84, v206
	v_xor_b32_e32 v203, v84, v207
	v_add_f32_dpp v90, v204, v200 row_shl:4 row_mask:0xf bank_mask:0x5
	v_add_f32_dpp v92, v205, v201 row_shl:4 row_mask:0xf bank_mask:0x5
	v_add_f32_dpp v89, v206, v202 row_shl:4 row_mask:0xf bank_mask:0x5
	v_add_f32_dpp v93, v207, v203 row_shl:4 row_mask:0xf bank_mask:0x5
	v_add_f32_dpp v90, v204, v200 row_shr:4 row_mask:0xf bank_mask:0xa
	v_add_f32_dpp v92, v205, v201 row_shr:4 row_mask:0xf bank_mask:0xa
	v_add_f32_dpp v89, v206, v202 row_shr:4 row_mask:0xf bank_mask:0xa
	v_add_f32_dpp v93, v207, v203 row_shr:4 row_mask:0xf bank_mask:0xa
	v_max_f32_e64 v88, |v90|, |v92|
	v_max_f32_e64 v98, |v89|, |v93|
	v_max3_f32 v91, v91, v88, v98
	v_cvt_pk_bf16_f32 v88, v90, v92
	v_cvt_pk_bf16_f32 v89, v89, v93
	s_waitcnt vmcnt(25)
	v_lshlrev_b32_e32 v90, 16, v94
	v_and_b32_e32 v92, 0xffff0000, v94
	v_lshlrev_b32_e32 v93, 16, v95
	v_and_b32_e32 v94, 0xffff0000, v95
	v_add_f32_e32 v95, v90, v92
	v_sub_f32_e32 v90, v90, v92
	v_add_f32_e32 v92, v93, v94
	v_sub_f32_e32 v93, v93, v94
	v_add_f32_e32 v94, v95, v92
	v_sub_f32_e32 v92, v95, v92
	v_add_f32_e32 v98, v90, v93
	v_sub_f32_e32 v90, v90, v93
	v_xor_b32_e32 v93, v82, v94
	v_xor_b32_e32 v95, v82, v92
	s_nop 0
	v_add_f32_dpp v93, v94, v93 quad_perm:[1,0,3,2] row_mask:0xf bank_mask:0xf bound_ctrl:1
	v_xor_b32_e32 v94, v82, v98
	v_add_f32_dpp v92, v92, v95 quad_perm:[1,0,3,2] row_mask:0xf bank_mask:0xf bound_ctrl:1
	v_xor_b32_e32 v95, v82, v90
	v_add_f32_dpp v94, v98, v94 quad_perm:[1,0,3,2] row_mask:0xf bank_mask:0xf bound_ctrl:1
	s_nop 0
	v_add_f32_dpp v90, v90, v95 quad_perm:[1,0,3,2] row_mask:0xf bank_mask:0xf bound_ctrl:1
	v_xor_b32_e32 v200, v83, v93
	v_xor_b32_e32 v201, v83, v94
	v_xor_b32_e32 v202, v83, v92
	v_xor_b32_e32 v203, v83, v90
	v_add_f32_dpp v204, v93, v200 quad_perm:[2,3,0,1] row_mask:0xf bank_mask:0xf bound_ctrl:1
	v_add_f32_dpp v205, v94, v201 quad_perm:[2,3,0,1] row_mask:0xf bank_mask:0xf bound_ctrl:1
	v_add_f32_dpp v206, v92, v202 quad_perm:[2,3,0,1] row_mask:0xf bank_mask:0xf bound_ctrl:1
	v_add_f32_dpp v207, v90, v203 quad_perm:[2,3,0,1] row_mask:0xf bank_mask:0xf bound_ctrl:1
	v_xor_b32_e32 v200, v84, v204
	v_xor_b32_e32 v201, v84, v205
	v_xor_b32_e32 v202, v84, v206
	v_xor_b32_e32 v203, v84, v207
	v_add_f32_dpp v93, v204, v200 row_shl:4 row_mask:0xf bank_mask:0x5
	v_add_f32_dpp v94, v205, v201 row_shl:4 row_mask:0xf bank_mask:0x5
	v_add_f32_dpp v92, v206, v202 row_shl:4 row_mask:0xf bank_mask:0x5
	v_add_f32_dpp v95, v207, v203 row_shl:4 row_mask:0xf bank_mask:0x5
	v_add_f32_dpp v93, v204, v200 row_shr:4 row_mask:0xf bank_mask:0xa
	v_add_f32_dpp v94, v205, v201 row_shr:4 row_mask:0xf bank_mask:0xa
	v_add_f32_dpp v92, v206, v202 row_shr:4 row_mask:0xf bank_mask:0xa
	v_add_f32_dpp v95, v207, v203 row_shr:4 row_mask:0xf bank_mask:0xa
	v_max_f32_e64 v90, |v93|, |v94|
	v_max_f32_e64 v98, |v92|, |v95|
	v_max3_f32 v98, v91, v90, v98
	v_cvt_pk_bf16_f32 v90, v93, v94
	v_cvt_pk_bf16_f32 v91, v92, v95
	s_waitcnt vmcnt(24)
	v_lshlrev_b32_e32 v92, 16, v96
	v_and_b32_e32 v93, 0xffff0000, v96
	v_lshlrev_b32_e32 v94, 16, v97
	v_and_b32_e32 v95, 0xffff0000, v97
	v_add_f32_e32 v96, v92, v93
	v_sub_f32_e32 v92, v92, v93
	v_add_f32_e32 v93, v94, v95
	v_sub_f32_e32 v94, v94, v95
	v_add_f32_e32 v95, v96, v93
	v_sub_f32_e32 v93, v96, v93
	v_add_f32_e32 v97, v92, v94
	v_sub_f32_e32 v92, v92, v94
	v_xor_b32_e32 v94, v82, v95
	v_xor_b32_e32 v96, v82, v93
	s_nop 0
	v_add_f32_dpp v94, v95, v94 quad_perm:[1,0,3,2] row_mask:0xf bank_mask:0xf bound_ctrl:1
	v_xor_b32_e32 v95, v82, v97
	v_add_f32_dpp v93, v93, v96 quad_perm:[1,0,3,2] row_mask:0xf bank_mask:0xf bound_ctrl:1
	v_xor_b32_e32 v96, v82, v92
	v_add_f32_dpp v95, v97, v95 quad_perm:[1,0,3,2] row_mask:0xf bank_mask:0xf bound_ctrl:1
	s_nop 0
	v_add_f32_dpp v92, v92, v96 quad_perm:[1,0,3,2] row_mask:0xf bank_mask:0xf bound_ctrl:1
	v_xor_b32_e32 v200, v83, v94
	v_xor_b32_e32 v201, v83, v95
	v_xor_b32_e32 v202, v83, v93
	v_xor_b32_e32 v203, v83, v92
	v_add_f32_dpp v204, v94, v200 quad_perm:[2,3,0,1] row_mask:0xf bank_mask:0xf bound_ctrl:1
	v_add_f32_dpp v205, v95, v201 quad_perm:[2,3,0,1] row_mask:0xf bank_mask:0xf bound_ctrl:1
	v_add_f32_dpp v206, v93, v202 quad_perm:[2,3,0,1] row_mask:0xf bank_mask:0xf bound_ctrl:1
	v_add_f32_dpp v207, v92, v203 quad_perm:[2,3,0,1] row_mask:0xf bank_mask:0xf bound_ctrl:1
	v_xor_b32_e32 v200, v84, v204
	v_xor_b32_e32 v201, v84, v205
	v_xor_b32_e32 v202, v84, v206
	v_xor_b32_e32 v203, v84, v207
	v_add_f32_dpp v94, v204, v200 row_shl:4 row_mask:0xf bank_mask:0x5
	v_add_f32_dpp v95, v205, v201 row_shl:4 row_mask:0xf bank_mask:0x5
	v_add_f32_dpp v93, v206, v202 row_shl:4 row_mask:0xf bank_mask:0x5
	v_add_f32_dpp v96, v207, v203 row_shl:4 row_mask:0xf bank_mask:0x5
	v_add_f32_dpp v94, v204, v200 row_shr:4 row_mask:0xf bank_mask:0xa
	v_add_f32_dpp v95, v205, v201 row_shr:4 row_mask:0xf bank_mask:0xa
	v_add_f32_dpp v93, v206, v202 row_shr:4 row_mask:0xf bank_mask:0xa
	v_add_f32_dpp v96, v207, v203 row_shr:4 row_mask:0xf bank_mask:0xa
	v_max_f32_e64 v92, |v94|, |v95|
	v_max_f32_e64 v97, |v93|, |v96|
	v_max3_f32 v97, v98, v92, v97
	v_cvt_pk_bf16_f32 v92, v94, v95
	s_waitcnt vmcnt(23)
	v_lshlrev_b32_e32 v94, 16, v80
	v_and_b32_e32 v80, 0xffff0000, v80
	v_lshlrev_b32_e32 v95, 16, v81
	v_and_b32_e32 v81, 0xffff0000, v81
	v_cvt_pk_bf16_f32 v93, v93, v96
	v_add_f32_e32 v96, v94, v80
	v_sub_f32_e32 v80, v94, v80
	v_add_f32_e32 v94, v95, v81
	v_sub_f32_e32 v81, v95, v81
	v_add_f32_e32 v95, v96, v94
	v_sub_f32_e32 v94, v96, v94
	v_add_f32_e32 v98, v80, v81
	v_sub_f32_e32 v80, v80, v81
	v_xor_b32_e32 v81, v82, v95
	v_xor_b32_e32 v96, v82, v94
	s_nop 0
	v_add_f32_dpp v81, v95, v81 quad_perm:[1,0,3,2] row_mask:0xf bank_mask:0xf bound_ctrl:1
	v_xor_b32_e32 v95, v82, v98
	v_add_f32_dpp v94, v94, v96 quad_perm:[1,0,3,2] row_mask:0xf bank_mask:0xf bound_ctrl:1
	v_xor_b32_e32 v96, v82, v80
	v_add_f32_dpp v95, v98, v95 quad_perm:[1,0,3,2] row_mask:0xf bank_mask:0xf bound_ctrl:1
	s_nop 0
	v_add_f32_dpp v80, v80, v96 quad_perm:[1,0,3,2] row_mask:0xf bank_mask:0xf bound_ctrl:1
	v_xor_b32_e32 v200, v83, v81
	v_xor_b32_e32 v201, v83, v95
	v_xor_b32_e32 v202, v83, v94
	v_xor_b32_e32 v203, v83, v80
	v_add_f32_dpp v204, v81, v200 quad_perm:[2,3,0,1] row_mask:0xf bank_mask:0xf bound_ctrl:1
	v_add_f32_dpp v205, v95, v201 quad_perm:[2,3,0,1] row_mask:0xf bank_mask:0xf bound_ctrl:1
	v_add_f32_dpp v206, v94, v202 quad_perm:[2,3,0,1] row_mask:0xf bank_mask:0xf bound_ctrl:1
	v_add_f32_dpp v207, v80, v203 quad_perm:[2,3,0,1] row_mask:0xf bank_mask:0xf bound_ctrl:1
	v_xor_b32_e32 v200, v84, v204
	v_xor_b32_e32 v201, v84, v205
	v_xor_b32_e32 v202, v84, v206
	v_xor_b32_e32 v203, v84, v207
	v_add_f32_dpp v81, v204, v200 row_shl:4 row_mask:0xf bank_mask:0x5
	v_add_f32_dpp v95, v205, v201 row_shl:4 row_mask:0xf bank_mask:0x5
	v_add_f32_dpp v94, v206, v202 row_shl:4 row_mask:0xf bank_mask:0x5
	v_add_f32_dpp v96, v207, v203 row_shl:4 row_mask:0xf bank_mask:0x5
	v_add_f32_dpp v81, v204, v200 row_shr:4 row_mask:0xf bank_mask:0xa
	v_add_f32_dpp v95, v205, v201 row_shr:4 row_mask:0xf bank_mask:0xa
	v_add_f32_dpp v94, v206, v202 row_shr:4 row_mask:0xf bank_mask:0xa
	v_add_f32_dpp v96, v207, v203 row_shr:4 row_mask:0xf bank_mask:0xa
	v_max_f32_e64 v80, |v81|, |v95|
	v_max_f32_e64 v98, |v94|, |v96|
	v_max3_f32 v97, v97, v80, v98
	v_cvt_pk_bf16_f32 v80, v81, v95
	v_cvt_pk_bf16_f32 v81, v94, v96
	s_waitcnt vmcnt(22)
	v_lshlrev_b32_e32 v94, 16, v78
	v_and_b32_e32 v78, 0xffff0000, v78
	v_lshlrev_b32_e32 v95, 16, v79
	v_and_b32_e32 v79, 0xffff0000, v79
	v_add_f32_e32 v96, v94, v78
	v_sub_f32_e32 v78, v94, v78
	v_add_f32_e32 v94, v95, v79
	v_sub_f32_e32 v79, v95, v79
	v_add_f32_e32 v95, v96, v94
	v_sub_f32_e32 v94, v96, v94
	v_add_f32_e32 v98, v78, v79
	v_sub_f32_e32 v78, v78, v79
	v_xor_b32_e32 v79, v82, v95
	v_xor_b32_e32 v96, v82, v94
	s_nop 0
	v_add_f32_dpp v79, v95, v79 quad_perm:[1,0,3,2] row_mask:0xf bank_mask:0xf bound_ctrl:1
	v_xor_b32_e32 v95, v82, v98
	v_add_f32_dpp v94, v94, v96 quad_perm:[1,0,3,2] row_mask:0xf bank_mask:0xf bound_ctrl:1
	v_xor_b32_e32 v96, v82, v78
	v_add_f32_dpp v95, v98, v95 quad_perm:[1,0,3,2] row_mask:0xf bank_mask:0xf bound_ctrl:1
	s_nop 0
	v_add_f32_dpp v78, v78, v96 quad_perm:[1,0,3,2] row_mask:0xf bank_mask:0xf bound_ctrl:1
	v_xor_b32_e32 v200, v83, v79
	v_xor_b32_e32 v201, v83, v95
	v_xor_b32_e32 v202, v83, v94
	v_xor_b32_e32 v203, v83, v78
	v_add_f32_dpp v204, v79, v200 quad_perm:[2,3,0,1] row_mask:0xf bank_mask:0xf bound_ctrl:1
	v_add_f32_dpp v205, v95, v201 quad_perm:[2,3,0,1] row_mask:0xf bank_mask:0xf bound_ctrl:1
	v_add_f32_dpp v206, v94, v202 quad_perm:[2,3,0,1] row_mask:0xf bank_mask:0xf bound_ctrl:1
	v_add_f32_dpp v207, v78, v203 quad_perm:[2,3,0,1] row_mask:0xf bank_mask:0xf bound_ctrl:1
	v_xor_b32_e32 v200, v84, v204
	v_xor_b32_e32 v201, v84, v205
	v_xor_b32_e32 v202, v84, v206
	v_xor_b32_e32 v203, v84, v207
	v_add_f32_dpp v79, v204, v200 row_shl:4 row_mask:0xf bank_mask:0x5
	v_add_f32_dpp v95, v205, v201 row_shl:4 row_mask:0xf bank_mask:0x5
	v_add_f32_dpp v94, v206, v202 row_shl:4 row_mask:0xf bank_mask:0x5
	v_add_f32_dpp v96, v207, v203 row_shl:4 row_mask:0xf bank_mask:0x5
	v_add_f32_dpp v79, v204, v200 row_shr:4 row_mask:0xf bank_mask:0xa
	v_add_f32_dpp v95, v205, v201 row_shr:4 row_mask:0xf bank_mask:0xa
	v_add_f32_dpp v94, v206, v202 row_shr:4 row_mask:0xf bank_mask:0xa
	v_add_f32_dpp v96, v207, v203 row_shr:4 row_mask:0xf bank_mask:0xa
	v_max_f32_e64 v78, |v79|, |v95|
	v_max_f32_e64 v98, |v94|, |v96|
	v_max3_f32 v97, v97, v78, v98
	v_cvt_pk_bf16_f32 v78, v79, v95
	v_cvt_pk_bf16_f32 v79, v94, v96
	s_waitcnt vmcnt(21)
	v_lshlrev_b32_e32 v94, 16, v76
	v_and_b32_e32 v76, 0xffff0000, v76
	v_lshlrev_b32_e32 v95, 16, v77
	v_and_b32_e32 v77, 0xffff0000, v77
	v_add_f32_e32 v96, v94, v76
	v_sub_f32_e32 v76, v94, v76
	v_add_f32_e32 v94, v95, v77
	v_sub_f32_e32 v77, v95, v77
	v_add_f32_e32 v95, v96, v94
	v_sub_f32_e32 v94, v96, v94
	v_add_f32_e32 v98, v76, v77
	v_sub_f32_e32 v76, v76, v77
	v_xor_b32_e32 v77, v82, v95
	v_xor_b32_e32 v96, v82, v94
	s_nop 0
	v_add_f32_dpp v77, v95, v77 quad_perm:[1,0,3,2] row_mask:0xf bank_mask:0xf bound_ctrl:1
	v_xor_b32_e32 v95, v82, v98
	v_add_f32_dpp v94, v94, v96 quad_perm:[1,0,3,2] row_mask:0xf bank_mask:0xf bound_ctrl:1
	v_xor_b32_e32 v96, v82, v76
	v_add_f32_dpp v95, v98, v95 quad_perm:[1,0,3,2] row_mask:0xf bank_mask:0xf bound_ctrl:1
	s_nop 0
	v_add_f32_dpp v76, v76, v96 quad_perm:[1,0,3,2] row_mask:0xf bank_mask:0xf bound_ctrl:1
	v_xor_b32_e32 v200, v83, v77
	v_xor_b32_e32 v201, v83, v95
	v_xor_b32_e32 v202, v83, v94
	v_xor_b32_e32 v203, v83, v76
	v_add_f32_dpp v204, v77, v200 quad_perm:[2,3,0,1] row_mask:0xf bank_mask:0xf bound_ctrl:1
	v_add_f32_dpp v205, v95, v201 quad_perm:[2,3,0,1] row_mask:0xf bank_mask:0xf bound_ctrl:1
	v_add_f32_dpp v206, v94, v202 quad_perm:[2,3,0,1] row_mask:0xf bank_mask:0xf bound_ctrl:1
	v_add_f32_dpp v207, v76, v203 quad_perm:[2,3,0,1] row_mask:0xf bank_mask:0xf bound_ctrl:1
	v_xor_b32_e32 v200, v84, v204
	v_xor_b32_e32 v201, v84, v205
	v_xor_b32_e32 v202, v84, v206
	v_xor_b32_e32 v203, v84, v207
	v_add_f32_dpp v77, v204, v200 row_shl:4 row_mask:0xf bank_mask:0x5
	v_add_f32_dpp v95, v205, v201 row_shl:4 row_mask:0xf bank_mask:0x5
	v_add_f32_dpp v94, v206, v202 row_shl:4 row_mask:0xf bank_mask:0x5
	v_add_f32_dpp v96, v207, v203 row_shl:4 row_mask:0xf bank_mask:0x5
	v_add_f32_dpp v77, v204, v200 row_shr:4 row_mask:0xf bank_mask:0xa
	v_add_f32_dpp v95, v205, v201 row_shr:4 row_mask:0xf bank_mask:0xa
	v_add_f32_dpp v94, v206, v202 row_shr:4 row_mask:0xf bank_mask:0xa
	v_add_f32_dpp v96, v207, v203 row_shr:4 row_mask:0xf bank_mask:0xa
	v_max_f32_e64 v76, |v77|, |v95|
	v_max_f32_e64 v98, |v94|, |v96|
	v_max3_f32 v97, v97, v76, v98
	v_cvt_pk_bf16_f32 v76, v77, v95
	v_cvt_pk_bf16_f32 v77, v94, v96
	s_waitcnt vmcnt(20)
	v_lshlrev_b32_e32 v94, 16, v74
	v_and_b32_e32 v74, 0xffff0000, v74
	v_lshlrev_b32_e32 v95, 16, v75
	v_and_b32_e32 v75, 0xffff0000, v75
	v_add_f32_e32 v96, v94, v74
	v_sub_f32_e32 v74, v94, v74
	v_add_f32_e32 v94, v95, v75
	v_sub_f32_e32 v75, v95, v75
	v_add_f32_e32 v95, v96, v94
	v_sub_f32_e32 v94, v96, v94
	v_add_f32_e32 v98, v74, v75
	v_sub_f32_e32 v74, v74, v75
	v_xor_b32_e32 v75, v82, v95
	v_xor_b32_e32 v96, v82, v94
	s_nop 0
	v_add_f32_dpp v75, v95, v75 quad_perm:[1,0,3,2] row_mask:0xf bank_mask:0xf bound_ctrl:1
	v_xor_b32_e32 v95, v82, v98
	v_add_f32_dpp v94, v94, v96 quad_perm:[1,0,3,2] row_mask:0xf bank_mask:0xf bound_ctrl:1
	v_xor_b32_e32 v96, v82, v74
	v_add_f32_dpp v95, v98, v95 quad_perm:[1,0,3,2] row_mask:0xf bank_mask:0xf bound_ctrl:1
	s_nop 0
	v_add_f32_dpp v74, v74, v96 quad_perm:[1,0,3,2] row_mask:0xf bank_mask:0xf bound_ctrl:1
	v_xor_b32_e32 v200, v83, v75
	v_xor_b32_e32 v201, v83, v95
	v_xor_b32_e32 v202, v83, v94
	v_xor_b32_e32 v203, v83, v74
	v_add_f32_dpp v204, v75, v200 quad_perm:[2,3,0,1] row_mask:0xf bank_mask:0xf bound_ctrl:1
	v_add_f32_dpp v205, v95, v201 quad_perm:[2,3,0,1] row_mask:0xf bank_mask:0xf bound_ctrl:1
	v_add_f32_dpp v206, v94, v202 quad_perm:[2,3,0,1] row_mask:0xf bank_mask:0xf bound_ctrl:1
	v_add_f32_dpp v207, v74, v203 quad_perm:[2,3,0,1] row_mask:0xf bank_mask:0xf bound_ctrl:1
	v_xor_b32_e32 v200, v84, v204
	v_xor_b32_e32 v201, v84, v205
	v_xor_b32_e32 v202, v84, v206
	v_xor_b32_e32 v203, v84, v207
	v_add_f32_dpp v75, v204, v200 row_shl:4 row_mask:0xf bank_mask:0x5
	v_add_f32_dpp v95, v205, v201 row_shl:4 row_mask:0xf bank_mask:0x5
	v_add_f32_dpp v94, v206, v202 row_shl:4 row_mask:0xf bank_mask:0x5
	v_add_f32_dpp v96, v207, v203 row_shl:4 row_mask:0xf bank_mask:0x5
	v_add_f32_dpp v75, v204, v200 row_shr:4 row_mask:0xf bank_mask:0xa
	v_add_f32_dpp v95, v205, v201 row_shr:4 row_mask:0xf bank_mask:0xa
	v_add_f32_dpp v94, v206, v202 row_shr:4 row_mask:0xf bank_mask:0xa
	v_add_f32_dpp v96, v207, v203 row_shr:4 row_mask:0xf bank_mask:0xa
	v_max_f32_e64 v74, |v75|, |v95|
	v_max_f32_e64 v98, |v94|, |v96|
	v_max3_f32 v97, v97, v74, v98
	v_cvt_pk_bf16_f32 v74, v75, v95
	v_cvt_pk_bf16_f32 v75, v94, v96
	s_waitcnt vmcnt(3)
	v_lshlrev_b32_e32 v94, 16, v72
	v_and_b32_e32 v72, 0xffff0000, v72
	v_lshlrev_b32_e32 v95, 16, v73
	v_and_b32_e32 v73, 0xffff0000, v73
	v_add_f32_e32 v96, v94, v72
	v_sub_f32_e32 v72, v94, v72
	v_add_f32_e32 v94, v95, v73
	v_sub_f32_e32 v73, v95, v73
	v_add_f32_e32 v95, v96, v94
	v_sub_f32_e32 v94, v96, v94
	v_add_f32_e32 v98, v72, v73
	v_sub_f32_e32 v72, v72, v73
	v_xor_b32_e32 v73, v82, v95
	v_xor_b32_e32 v96, v82, v94
	s_nop 0
	v_add_f32_dpp v73, v95, v73 quad_perm:[1,0,3,2] row_mask:0xf bank_mask:0xf bound_ctrl:1
	v_xor_b32_e32 v95, v82, v98
	v_add_f32_dpp v94, v94, v96 quad_perm:[1,0,3,2] row_mask:0xf bank_mask:0xf bound_ctrl:1
	v_xor_b32_e32 v96, v82, v72
	v_add_f32_dpp v95, v98, v95 quad_perm:[1,0,3,2] row_mask:0xf bank_mask:0xf bound_ctrl:1
	s_nop 0
	v_add_f32_dpp v72, v72, v96 quad_perm:[1,0,3,2] row_mask:0xf bank_mask:0xf bound_ctrl:1
	v_xor_b32_e32 v200, v83, v73
	v_xor_b32_e32 v201, v83, v95
	v_xor_b32_e32 v202, v83, v94
	v_xor_b32_e32 v203, v83, v72
	v_add_f32_dpp v204, v73, v200 quad_perm:[2,3,0,1] row_mask:0xf bank_mask:0xf bound_ctrl:1
	v_add_f32_dpp v205, v95, v201 quad_perm:[2,3,0,1] row_mask:0xf bank_mask:0xf bound_ctrl:1
	v_add_f32_dpp v206, v94, v202 quad_perm:[2,3,0,1] row_mask:0xf bank_mask:0xf bound_ctrl:1
	v_add_f32_dpp v207, v72, v203 quad_perm:[2,3,0,1] row_mask:0xf bank_mask:0xf bound_ctrl:1
	v_xor_b32_e32 v200, v84, v204
	v_xor_b32_e32 v201, v84, v205
	v_xor_b32_e32 v202, v84, v206
	v_xor_b32_e32 v203, v84, v207
	v_add_f32_dpp v73, v204, v200 row_shl:4 row_mask:0xf bank_mask:0x5
	v_add_f32_dpp v95, v205, v201 row_shl:4 row_mask:0xf bank_mask:0x5
	v_add_f32_dpp v94, v206, v202 row_shl:4 row_mask:0xf bank_mask:0x5
	v_add_f32_dpp v96, v207, v203 row_shl:4 row_mask:0xf bank_mask:0x5
	v_add_f32_dpp v73, v204, v200 row_shr:4 row_mask:0xf bank_mask:0xa
	v_add_f32_dpp v95, v205, v201 row_shr:4 row_mask:0xf bank_mask:0xa
	v_add_f32_dpp v94, v206, v202 row_shr:4 row_mask:0xf bank_mask:0xa
	v_add_f32_dpp v96, v207, v203 row_shr:4 row_mask:0xf bank_mask:0xa
	v_max_f32_e64 v72, |v73|, |v95|
	v_max_f32_e64 v98, |v94|, |v96|
	v_max3_f32 v97, v97, v72, v98
	v_cvt_pk_bf16_f32 v72, v73, v95
	v_cvt_pk_bf16_f32 v73, v94, v96
	v_lshlrev_b32_e32 v94, 16, v70
	v_and_b32_e32 v70, 0xffff0000, v70
	v_lshlrev_b32_e32 v95, 16, v71
	v_and_b32_e32 v71, 0xffff0000, v71
	v_add_f32_e32 v96, v94, v70
	v_sub_f32_e32 v70, v94, v70
	v_add_f32_e32 v94, v95, v71
	v_sub_f32_e32 v71, v95, v71
	v_add_f32_e32 v95, v96, v94
	v_sub_f32_e32 v94, v96, v94
	v_add_f32_e32 v98, v70, v71
	v_sub_f32_e32 v70, v70, v71
	v_xor_b32_e32 v71, v82, v95
	v_xor_b32_e32 v96, v82, v94
	s_nop 0
	v_add_f32_dpp v71, v95, v71 quad_perm:[1,0,3,2] row_mask:0xf bank_mask:0xf bound_ctrl:1
	v_xor_b32_e32 v95, v82, v98
	v_add_f32_dpp v94, v94, v96 quad_perm:[1,0,3,2] row_mask:0xf bank_mask:0xf bound_ctrl:1
	v_xor_b32_e32 v96, v82, v70
	v_add_f32_dpp v95, v98, v95 quad_perm:[1,0,3,2] row_mask:0xf bank_mask:0xf bound_ctrl:1
	s_nop 0
	v_add_f32_dpp v70, v70, v96 quad_perm:[1,0,3,2] row_mask:0xf bank_mask:0xf bound_ctrl:1
	v_xor_b32_e32 v200, v83, v71
	v_xor_b32_e32 v201, v83, v95
	v_xor_b32_e32 v202, v83, v94
	v_xor_b32_e32 v203, v83, v70
	v_add_f32_dpp v204, v71, v200 quad_perm:[2,3,0,1] row_mask:0xf bank_mask:0xf bound_ctrl:1
	v_add_f32_dpp v205, v95, v201 quad_perm:[2,3,0,1] row_mask:0xf bank_mask:0xf bound_ctrl:1
	v_add_f32_dpp v206, v94, v202 quad_perm:[2,3,0,1] row_mask:0xf bank_mask:0xf bound_ctrl:1
	v_add_f32_dpp v207, v70, v203 quad_perm:[2,3,0,1] row_mask:0xf bank_mask:0xf bound_ctrl:1
	v_xor_b32_e32 v200, v84, v204
	v_xor_b32_e32 v201, v84, v205
	v_xor_b32_e32 v202, v84, v206
	v_xor_b32_e32 v203, v84, v207
	v_add_f32_dpp v71, v204, v200 row_shl:4 row_mask:0xf bank_mask:0x5
	v_add_f32_dpp v95, v205, v201 row_shl:4 row_mask:0xf bank_mask:0x5
	v_add_f32_dpp v94, v206, v202 row_shl:4 row_mask:0xf bank_mask:0x5
	v_add_f32_dpp v96, v207, v203 row_shl:4 row_mask:0xf bank_mask:0x5
	v_add_f32_dpp v71, v204, v200 row_shr:4 row_mask:0xf bank_mask:0xa
	v_add_f32_dpp v95, v205, v201 row_shr:4 row_mask:0xf bank_mask:0xa
	v_add_f32_dpp v94, v206, v202 row_shr:4 row_mask:0xf bank_mask:0xa
	v_add_f32_dpp v96, v207, v203 row_shr:4 row_mask:0xf bank_mask:0xa
	v_max_f32_e64 v70, |v71|, |v95|
	v_max_f32_e64 v98, |v94|, |v96|
	v_max3_f32 v97, v97, v70, v98
	v_cvt_pk_bf16_f32 v70, v71, v95
	v_cvt_pk_bf16_f32 v71, v94, v96
	v_lshlrev_b32_e32 v94, 16, v68
	v_and_b32_e32 v68, 0xffff0000, v68
	v_lshlrev_b32_e32 v95, 16, v69
	v_and_b32_e32 v69, 0xffff0000, v69
	v_add_f32_e32 v96, v94, v68
	v_sub_f32_e32 v68, v94, v68
	v_add_f32_e32 v94, v95, v69
	v_sub_f32_e32 v69, v95, v69
	v_add_f32_e32 v95, v96, v94
	v_sub_f32_e32 v94, v96, v94
	v_add_f32_e32 v98, v68, v69
	v_sub_f32_e32 v68, v68, v69
	v_xor_b32_e32 v69, v82, v95
	v_xor_b32_e32 v96, v82, v94
	s_nop 0
	v_add_f32_dpp v69, v95, v69 quad_perm:[1,0,3,2] row_mask:0xf bank_mask:0xf bound_ctrl:1
	v_xor_b32_e32 v95, v82, v98
	v_add_f32_dpp v94, v94, v96 quad_perm:[1,0,3,2] row_mask:0xf bank_mask:0xf bound_ctrl:1
	v_xor_b32_e32 v96, v82, v68
	v_add_f32_dpp v95, v98, v95 quad_perm:[1,0,3,2] row_mask:0xf bank_mask:0xf bound_ctrl:1
	s_nop 0
	v_add_f32_dpp v68, v68, v96 quad_perm:[1,0,3,2] row_mask:0xf bank_mask:0xf bound_ctrl:1
	v_xor_b32_e32 v200, v83, v69
	v_xor_b32_e32 v201, v83, v95
	v_xor_b32_e32 v202, v83, v94
	v_xor_b32_e32 v203, v83, v68
	v_add_f32_dpp v204, v69, v200 quad_perm:[2,3,0,1] row_mask:0xf bank_mask:0xf bound_ctrl:1
	v_add_f32_dpp v205, v95, v201 quad_perm:[2,3,0,1] row_mask:0xf bank_mask:0xf bound_ctrl:1
	v_add_f32_dpp v206, v94, v202 quad_perm:[2,3,0,1] row_mask:0xf bank_mask:0xf bound_ctrl:1
	v_add_f32_dpp v207, v68, v203 quad_perm:[2,3,0,1] row_mask:0xf bank_mask:0xf bound_ctrl:1
	v_xor_b32_e32 v200, v84, v204
	v_xor_b32_e32 v201, v84, v205
	v_xor_b32_e32 v202, v84, v206
	v_xor_b32_e32 v203, v84, v207
	v_add_f32_dpp v69, v204, v200 row_shl:4 row_mask:0xf bank_mask:0x5
	v_add_f32_dpp v95, v205, v201 row_shl:4 row_mask:0xf bank_mask:0x5
	v_add_f32_dpp v94, v206, v202 row_shl:4 row_mask:0xf bank_mask:0x5
	v_add_f32_dpp v96, v207, v203 row_shl:4 row_mask:0xf bank_mask:0x5
	v_add_f32_dpp v69, v204, v200 row_shr:4 row_mask:0xf bank_mask:0xa
	v_add_f32_dpp v95, v205, v201 row_shr:4 row_mask:0xf bank_mask:0xa
	v_add_f32_dpp v94, v206, v202 row_shr:4 row_mask:0xf bank_mask:0xa
	v_add_f32_dpp v96, v207, v203 row_shr:4 row_mask:0xf bank_mask:0xa
	v_max_f32_e64 v68, |v69|, |v95|
	v_max_f32_e64 v98, |v94|, |v96|
	v_max3_f32 v97, v97, v68, v98
	v_cvt_pk_bf16_f32 v68, v69, v95
	v_cvt_pk_bf16_f32 v69, v94, v96
	v_lshlrev_b32_e32 v94, 16, v66
	v_and_b32_e32 v66, 0xffff0000, v66
	v_lshlrev_b32_e32 v95, 16, v67
	v_and_b32_e32 v67, 0xffff0000, v67
	v_add_f32_e32 v96, v94, v66
	v_sub_f32_e32 v66, v94, v66
	v_add_f32_e32 v94, v95, v67
	v_sub_f32_e32 v67, v95, v67
	v_add_f32_e32 v95, v96, v94
	v_sub_f32_e32 v94, v96, v94
	v_add_f32_e32 v98, v66, v67
	v_sub_f32_e32 v66, v66, v67
	v_xor_b32_e32 v67, v82, v95
	v_xor_b32_e32 v96, v82, v94
	s_nop 0
	v_add_f32_dpp v67, v95, v67 quad_perm:[1,0,3,2] row_mask:0xf bank_mask:0xf bound_ctrl:1
	v_xor_b32_e32 v95, v82, v98
	v_add_f32_dpp v94, v94, v96 quad_perm:[1,0,3,2] row_mask:0xf bank_mask:0xf bound_ctrl:1
	v_xor_b32_e32 v96, v82, v66
	v_add_f32_dpp v95, v98, v95 quad_perm:[1,0,3,2] row_mask:0xf bank_mask:0xf bound_ctrl:1
	s_nop 0
	v_add_f32_dpp v66, v66, v96 quad_perm:[1,0,3,2] row_mask:0xf bank_mask:0xf bound_ctrl:1
	v_xor_b32_e32 v200, v83, v67
	v_xor_b32_e32 v201, v83, v95
	v_xor_b32_e32 v202, v83, v94
	v_xor_b32_e32 v203, v83, v66
	v_add_f32_dpp v204, v67, v200 quad_perm:[2,3,0,1] row_mask:0xf bank_mask:0xf bound_ctrl:1
	v_add_f32_dpp v205, v95, v201 quad_perm:[2,3,0,1] row_mask:0xf bank_mask:0xf bound_ctrl:1
	v_add_f32_dpp v206, v94, v202 quad_perm:[2,3,0,1] row_mask:0xf bank_mask:0xf bound_ctrl:1
	v_add_f32_dpp v207, v66, v203 quad_perm:[2,3,0,1] row_mask:0xf bank_mask:0xf bound_ctrl:1
	v_xor_b32_e32 v200, v84, v204
	v_xor_b32_e32 v201, v84, v205
	v_xor_b32_e32 v202, v84, v206
	v_xor_b32_e32 v203, v84, v207
	v_add_f32_dpp v67, v204, v200 row_shl:4 row_mask:0xf bank_mask:0x5
	v_add_f32_dpp v95, v205, v201 row_shl:4 row_mask:0xf bank_mask:0x5
	v_add_f32_dpp v94, v206, v202 row_shl:4 row_mask:0xf bank_mask:0x5
	v_add_f32_dpp v96, v207, v203 row_shl:4 row_mask:0xf bank_mask:0x5
	v_add_f32_dpp v67, v204, v200 row_shr:4 row_mask:0xf bank_mask:0xa
	v_add_f32_dpp v95, v205, v201 row_shr:4 row_mask:0xf bank_mask:0xa
	v_add_f32_dpp v94, v206, v202 row_shr:4 row_mask:0xf bank_mask:0xa
	v_add_f32_dpp v96, v207, v203 row_shr:4 row_mask:0xf bank_mask:0xa
	v_max_f32_e64 v66, |v67|, |v95|
	v_max_f32_e64 v98, |v94|, |v96|
	v_max3_f32 v97, v97, v66, v98
	v_cvt_pk_bf16_f32 v66, v67, v95
	v_cvt_pk_bf16_f32 v67, v94, v96
	v_lshlrev_b32_e32 v94, 16, v64
	v_and_b32_e32 v64, 0xffff0000, v64
	v_lshlrev_b32_e32 v95, 16, v65
	v_and_b32_e32 v65, 0xffff0000, v65
	v_add_f32_e32 v96, v94, v64
	v_sub_f32_e32 v64, v94, v64
	v_add_f32_e32 v94, v95, v65
	v_sub_f32_e32 v65, v95, v65
	v_add_f32_e32 v95, v96, v94
	v_sub_f32_e32 v94, v96, v94
	v_add_f32_e32 v98, v64, v65
	v_sub_f32_e32 v64, v64, v65
	v_xor_b32_e32 v65, v82, v95
	v_xor_b32_e32 v96, v82, v94
	s_nop 0
	v_add_f32_dpp v65, v95, v65 quad_perm:[1,0,3,2] row_mask:0xf bank_mask:0xf bound_ctrl:1
	v_xor_b32_e32 v95, v82, v98
	v_add_f32_dpp v94, v94, v96 quad_perm:[1,0,3,2] row_mask:0xf bank_mask:0xf bound_ctrl:1
	v_xor_b32_e32 v96, v82, v64
	v_add_f32_dpp v95, v98, v95 quad_perm:[1,0,3,2] row_mask:0xf bank_mask:0xf bound_ctrl:1
	s_nop 0
	v_add_f32_dpp v64, v64, v96 quad_perm:[1,0,3,2] row_mask:0xf bank_mask:0xf bound_ctrl:1
	v_xor_b32_e32 v200, v83, v65
	v_xor_b32_e32 v201, v83, v95
	v_xor_b32_e32 v202, v83, v94
	v_xor_b32_e32 v203, v83, v64
	v_add_f32_dpp v204, v65, v200 quad_perm:[2,3,0,1] row_mask:0xf bank_mask:0xf bound_ctrl:1
	v_add_f32_dpp v205, v95, v201 quad_perm:[2,3,0,1] row_mask:0xf bank_mask:0xf bound_ctrl:1
	v_add_f32_dpp v206, v94, v202 quad_perm:[2,3,0,1] row_mask:0xf bank_mask:0xf bound_ctrl:1
	v_add_f32_dpp v207, v64, v203 quad_perm:[2,3,0,1] row_mask:0xf bank_mask:0xf bound_ctrl:1
	v_xor_b32_e32 v200, v84, v204
	v_xor_b32_e32 v201, v84, v205
	v_xor_b32_e32 v202, v84, v206
	v_xor_b32_e32 v203, v84, v207
	v_add_f32_dpp v65, v204, v200 row_shl:4 row_mask:0xf bank_mask:0x5
	v_add_f32_dpp v95, v205, v201 row_shl:4 row_mask:0xf bank_mask:0x5
	v_add_f32_dpp v94, v206, v202 row_shl:4 row_mask:0xf bank_mask:0x5
	v_add_f32_dpp v96, v207, v203 row_shl:4 row_mask:0xf bank_mask:0x5
	v_add_f32_dpp v65, v204, v200 row_shr:4 row_mask:0xf bank_mask:0xa
	v_add_f32_dpp v95, v205, v201 row_shr:4 row_mask:0xf bank_mask:0xa
	v_add_f32_dpp v94, v206, v202 row_shr:4 row_mask:0xf bank_mask:0xa
	v_add_f32_dpp v96, v207, v203 row_shr:4 row_mask:0xf bank_mask:0xa
	v_max_f32_e64 v64, |v65|, |v95|
	v_max_f32_e64 v98, |v94|, |v96|
	v_max3_f32 v97, v97, v64, v98
	v_cvt_pk_bf16_f32 v64, v65, v95
	v_cvt_pk_bf16_f32 v65, v94, v96
	v_lshlrev_b32_e32 v94, 16, v62
	v_and_b32_e32 v62, 0xffff0000, v62
	v_lshlrev_b32_e32 v95, 16, v63
	v_and_b32_e32 v63, 0xffff0000, v63
	v_add_f32_e32 v96, v94, v62
	v_sub_f32_e32 v62, v94, v62
	v_add_f32_e32 v94, v95, v63
	v_sub_f32_e32 v63, v95, v63
	v_add_f32_e32 v95, v96, v94
	v_sub_f32_e32 v94, v96, v94
	v_add_f32_e32 v98, v62, v63
	v_sub_f32_e32 v62, v62, v63
	v_xor_b32_e32 v63, v82, v95
	v_xor_b32_e32 v96, v82, v94
	s_nop 0
	v_add_f32_dpp v63, v95, v63 quad_perm:[1,0,3,2] row_mask:0xf bank_mask:0xf bound_ctrl:1
	v_xor_b32_e32 v95, v82, v98
	v_add_f32_dpp v94, v94, v96 quad_perm:[1,0,3,2] row_mask:0xf bank_mask:0xf bound_ctrl:1
	v_xor_b32_e32 v96, v82, v62
	v_add_f32_dpp v95, v98, v95 quad_perm:[1,0,3,2] row_mask:0xf bank_mask:0xf bound_ctrl:1
	s_nop 0
	v_add_f32_dpp v62, v62, v96 quad_perm:[1,0,3,2] row_mask:0xf bank_mask:0xf bound_ctrl:1
	v_xor_b32_e32 v200, v83, v63
	v_xor_b32_e32 v201, v83, v95
	v_xor_b32_e32 v202, v83, v94
	v_xor_b32_e32 v203, v83, v62
	v_add_f32_dpp v204, v63, v200 quad_perm:[2,3,0,1] row_mask:0xf bank_mask:0xf bound_ctrl:1
	v_add_f32_dpp v205, v95, v201 quad_perm:[2,3,0,1] row_mask:0xf bank_mask:0xf bound_ctrl:1
	v_add_f32_dpp v206, v94, v202 quad_perm:[2,3,0,1] row_mask:0xf bank_mask:0xf bound_ctrl:1
	v_add_f32_dpp v207, v62, v203 quad_perm:[2,3,0,1] row_mask:0xf bank_mask:0xf bound_ctrl:1
	v_xor_b32_e32 v200, v84, v204
	v_xor_b32_e32 v201, v84, v205
	v_xor_b32_e32 v202, v84, v206
	v_xor_b32_e32 v203, v84, v207
	v_add_f32_dpp v63, v204, v200 row_shl:4 row_mask:0xf bank_mask:0x5
	v_add_f32_dpp v95, v205, v201 row_shl:4 row_mask:0xf bank_mask:0x5
	v_add_f32_dpp v94, v206, v202 row_shl:4 row_mask:0xf bank_mask:0x5
	v_add_f32_dpp v96, v207, v203 row_shl:4 row_mask:0xf bank_mask:0x5
	v_add_f32_dpp v63, v204, v200 row_shr:4 row_mask:0xf bank_mask:0xa
	v_add_f32_dpp v95, v205, v201 row_shr:4 row_mask:0xf bank_mask:0xa
	v_add_f32_dpp v94, v206, v202 row_shr:4 row_mask:0xf bank_mask:0xa
	v_add_f32_dpp v96, v207, v203 row_shr:4 row_mask:0xf bank_mask:0xa
	v_max_f32_e64 v62, |v63|, |v95|
	v_max_f32_e64 v98, |v94|, |v96|
	v_max3_f32 v97, v97, v62, v98
	v_cvt_pk_bf16_f32 v62, v63, v95
	v_cvt_pk_bf16_f32 v63, v94, v96
	v_lshlrev_b32_e32 v94, 16, v60
	v_and_b32_e32 v60, 0xffff0000, v60
	v_lshlrev_b32_e32 v95, 16, v61
	v_and_b32_e32 v61, 0xffff0000, v61
	v_add_f32_e32 v96, v94, v60
	v_sub_f32_e32 v60, v94, v60
	v_add_f32_e32 v94, v95, v61
	v_sub_f32_e32 v61, v95, v61
	v_add_f32_e32 v95, v96, v94
	v_sub_f32_e32 v94, v96, v94
	v_add_f32_e32 v98, v60, v61
	v_sub_f32_e32 v60, v60, v61
	v_xor_b32_e32 v61, v82, v95
	v_xor_b32_e32 v96, v82, v94
	s_nop 0
	v_add_f32_dpp v61, v95, v61 quad_perm:[1,0,3,2] row_mask:0xf bank_mask:0xf bound_ctrl:1
	v_xor_b32_e32 v95, v82, v98
	v_add_f32_dpp v94, v94, v96 quad_perm:[1,0,3,2] row_mask:0xf bank_mask:0xf bound_ctrl:1
	v_xor_b32_e32 v96, v82, v60
	v_add_f32_dpp v95, v98, v95 quad_perm:[1,0,3,2] row_mask:0xf bank_mask:0xf bound_ctrl:1
	s_nop 0
	v_add_f32_dpp v60, v60, v96 quad_perm:[1,0,3,2] row_mask:0xf bank_mask:0xf bound_ctrl:1
	v_xor_b32_e32 v200, v83, v61
	v_xor_b32_e32 v201, v83, v95
	v_xor_b32_e32 v202, v83, v94
	v_xor_b32_e32 v203, v83, v60
	v_add_f32_dpp v204, v61, v200 quad_perm:[2,3,0,1] row_mask:0xf bank_mask:0xf bound_ctrl:1
	v_add_f32_dpp v205, v95, v201 quad_perm:[2,3,0,1] row_mask:0xf bank_mask:0xf bound_ctrl:1
	v_add_f32_dpp v206, v94, v202 quad_perm:[2,3,0,1] row_mask:0xf bank_mask:0xf bound_ctrl:1
	v_add_f32_dpp v207, v60, v203 quad_perm:[2,3,0,1] row_mask:0xf bank_mask:0xf bound_ctrl:1
	v_xor_b32_e32 v200, v84, v204
	v_xor_b32_e32 v201, v84, v205
	v_xor_b32_e32 v202, v84, v206
	v_xor_b32_e32 v203, v84, v207
	v_add_f32_dpp v61, v204, v200 row_shl:4 row_mask:0xf bank_mask:0x5
	v_add_f32_dpp v95, v205, v201 row_shl:4 row_mask:0xf bank_mask:0x5
	v_add_f32_dpp v94, v206, v202 row_shl:4 row_mask:0xf bank_mask:0x5
	v_add_f32_dpp v96, v207, v203 row_shl:4 row_mask:0xf bank_mask:0x5
	v_add_f32_dpp v61, v204, v200 row_shr:4 row_mask:0xf bank_mask:0xa
	v_add_f32_dpp v95, v205, v201 row_shr:4 row_mask:0xf bank_mask:0xa
	v_add_f32_dpp v94, v206, v202 row_shr:4 row_mask:0xf bank_mask:0xa
	v_add_f32_dpp v96, v207, v203 row_shr:4 row_mask:0xf bank_mask:0xa
	v_max_f32_e64 v60, |v61|, |v95|
	v_max_f32_e64 v98, |v94|, |v96|
	v_max3_f32 v97, v97, v60, v98
	v_cvt_pk_bf16_f32 v60, v61, v95
	v_cvt_pk_bf16_f32 v61, v94, v96
	v_lshlrev_b32_e32 v94, 16, v58
	v_and_b32_e32 v58, 0xffff0000, v58
	v_lshlrev_b32_e32 v95, 16, v59
	v_and_b32_e32 v59, 0xffff0000, v59
	v_add_f32_e32 v96, v94, v58
	v_sub_f32_e32 v58, v94, v58
	v_add_f32_e32 v94, v95, v59
	v_sub_f32_e32 v59, v95, v59
	v_add_f32_e32 v95, v96, v94
	v_sub_f32_e32 v94, v96, v94
	v_add_f32_e32 v98, v58, v59
	v_sub_f32_e32 v58, v58, v59
	v_xor_b32_e32 v59, v82, v95
	v_xor_b32_e32 v96, v82, v94
	s_nop 0
	v_add_f32_dpp v59, v95, v59 quad_perm:[1,0,3,2] row_mask:0xf bank_mask:0xf bound_ctrl:1
	v_xor_b32_e32 v95, v82, v98
	v_add_f32_dpp v94, v94, v96 quad_perm:[1,0,3,2] row_mask:0xf bank_mask:0xf bound_ctrl:1
	v_xor_b32_e32 v96, v82, v58
	v_add_f32_dpp v95, v98, v95 quad_perm:[1,0,3,2] row_mask:0xf bank_mask:0xf bound_ctrl:1
	s_nop 0
	v_add_f32_dpp v58, v58, v96 quad_perm:[1,0,3,2] row_mask:0xf bank_mask:0xf bound_ctrl:1
	v_xor_b32_e32 v200, v83, v59
	v_xor_b32_e32 v201, v83, v95
	v_xor_b32_e32 v202, v83, v94
	v_xor_b32_e32 v203, v83, v58
	v_add_f32_dpp v204, v59, v200 quad_perm:[2,3,0,1] row_mask:0xf bank_mask:0xf bound_ctrl:1
	v_add_f32_dpp v205, v95, v201 quad_perm:[2,3,0,1] row_mask:0xf bank_mask:0xf bound_ctrl:1
	v_add_f32_dpp v206, v94, v202 quad_perm:[2,3,0,1] row_mask:0xf bank_mask:0xf bound_ctrl:1
	v_add_f32_dpp v207, v58, v203 quad_perm:[2,3,0,1] row_mask:0xf bank_mask:0xf bound_ctrl:1
	v_xor_b32_e32 v200, v84, v204
	v_xor_b32_e32 v201, v84, v205
	v_xor_b32_e32 v202, v84, v206
	v_xor_b32_e32 v203, v84, v207
	v_add_f32_dpp v59, v204, v200 row_shl:4 row_mask:0xf bank_mask:0x5
	v_add_f32_dpp v95, v205, v201 row_shl:4 row_mask:0xf bank_mask:0x5
	v_add_f32_dpp v94, v206, v202 row_shl:4 row_mask:0xf bank_mask:0x5
	v_add_f32_dpp v96, v207, v203 row_shl:4 row_mask:0xf bank_mask:0x5
	v_add_f32_dpp v59, v204, v200 row_shr:4 row_mask:0xf bank_mask:0xa
	v_add_f32_dpp v95, v205, v201 row_shr:4 row_mask:0xf bank_mask:0xa
	v_add_f32_dpp v94, v206, v202 row_shr:4 row_mask:0xf bank_mask:0xa
	v_add_f32_dpp v96, v207, v203 row_shr:4 row_mask:0xf bank_mask:0xa
	v_max_f32_e64 v58, |v59|, |v95|
	v_max_f32_e64 v98, |v94|, |v96|
	v_max3_f32 v97, v97, v58, v98
	v_cvt_pk_bf16_f32 v58, v59, v95
	v_cvt_pk_bf16_f32 v59, v94, v96
	s_waitcnt vmcnt(2)
	v_lshlrev_b32_e32 v94, 16, v56
	v_and_b32_e32 v56, 0xffff0000, v56
	v_lshlrev_b32_e32 v95, 16, v57
	v_and_b32_e32 v57, 0xffff0000, v57
	v_add_f32_e32 v96, v94, v56
	v_sub_f32_e32 v56, v94, v56
	v_add_f32_e32 v94, v95, v57
	v_sub_f32_e32 v57, v95, v57
	v_add_f32_e32 v95, v96, v94
	v_sub_f32_e32 v94, v96, v94
	v_add_f32_e32 v98, v56, v57
	v_sub_f32_e32 v56, v56, v57
	v_xor_b32_e32 v57, v82, v95
	v_xor_b32_e32 v96, v82, v94
	s_nop 0
	v_add_f32_dpp v57, v95, v57 quad_perm:[1,0,3,2] row_mask:0xf bank_mask:0xf bound_ctrl:1
	v_xor_b32_e32 v95, v82, v98
	v_add_f32_dpp v94, v94, v96 quad_perm:[1,0,3,2] row_mask:0xf bank_mask:0xf bound_ctrl:1
	v_xor_b32_e32 v96, v82, v56
	v_add_f32_dpp v95, v98, v95 quad_perm:[1,0,3,2] row_mask:0xf bank_mask:0xf bound_ctrl:1
	s_nop 0
	v_add_f32_dpp v56, v56, v96 quad_perm:[1,0,3,2] row_mask:0xf bank_mask:0xf bound_ctrl:1
	v_xor_b32_e32 v200, v83, v57
	v_xor_b32_e32 v201, v83, v95
	v_xor_b32_e32 v202, v83, v94
	v_xor_b32_e32 v203, v83, v56
	v_add_f32_dpp v204, v57, v200 quad_perm:[2,3,0,1] row_mask:0xf bank_mask:0xf bound_ctrl:1
	v_add_f32_dpp v205, v95, v201 quad_perm:[2,3,0,1] row_mask:0xf bank_mask:0xf bound_ctrl:1
	v_add_f32_dpp v206, v94, v202 quad_perm:[2,3,0,1] row_mask:0xf bank_mask:0xf bound_ctrl:1
	v_add_f32_dpp v207, v56, v203 quad_perm:[2,3,0,1] row_mask:0xf bank_mask:0xf bound_ctrl:1
	v_xor_b32_e32 v200, v84, v204
	v_xor_b32_e32 v201, v84, v205
	v_xor_b32_e32 v202, v84, v206
	v_xor_b32_e32 v203, v84, v207
	v_add_f32_dpp v57, v204, v200 row_shl:4 row_mask:0xf bank_mask:0x5
	v_add_f32_dpp v95, v205, v201 row_shl:4 row_mask:0xf bank_mask:0x5
	v_add_f32_dpp v94, v206, v202 row_shl:4 row_mask:0xf bank_mask:0x5
	v_add_f32_dpp v96, v207, v203 row_shl:4 row_mask:0xf bank_mask:0x5
	v_add_f32_dpp v57, v204, v200 row_shr:4 row_mask:0xf bank_mask:0xa
	v_add_f32_dpp v95, v205, v201 row_shr:4 row_mask:0xf bank_mask:0xa
	v_add_f32_dpp v94, v206, v202 row_shr:4 row_mask:0xf bank_mask:0xa
	v_add_f32_dpp v96, v207, v203 row_shr:4 row_mask:0xf bank_mask:0xa
	v_max_f32_e64 v56, |v57|, |v95|
	v_max_f32_e64 v98, |v94|, |v96|
	v_max3_f32 v97, v97, v56, v98
	v_cvt_pk_bf16_f32 v56, v57, v95
	v_cvt_pk_bf16_f32 v57, v94, v96
	s_waitcnt vmcnt(1)
	v_lshlrev_b32_e32 v94, 16, v54
	v_and_b32_e32 v54, 0xffff0000, v54
	v_lshlrev_b32_e32 v95, 16, v55
	v_and_b32_e32 v55, 0xffff0000, v55
	v_add_f32_e32 v96, v94, v54
	v_sub_f32_e32 v54, v94, v54
	v_add_f32_e32 v94, v95, v55
	v_sub_f32_e32 v55, v95, v55
	v_add_f32_e32 v95, v96, v94
	v_sub_f32_e32 v94, v96, v94
	v_add_f32_e32 v98, v54, v55
	v_sub_f32_e32 v54, v54, v55
	v_xor_b32_e32 v55, v82, v95
	v_xor_b32_e32 v96, v82, v94
	s_nop 0
	v_add_f32_dpp v55, v95, v55 quad_perm:[1,0,3,2] row_mask:0xf bank_mask:0xf bound_ctrl:1
	v_xor_b32_e32 v95, v82, v98
	v_add_f32_dpp v94, v94, v96 quad_perm:[1,0,3,2] row_mask:0xf bank_mask:0xf bound_ctrl:1
	v_xor_b32_e32 v96, v82, v54
	v_add_f32_dpp v95, v98, v95 quad_perm:[1,0,3,2] row_mask:0xf bank_mask:0xf bound_ctrl:1
	s_nop 0
	v_add_f32_dpp v54, v54, v96 quad_perm:[1,0,3,2] row_mask:0xf bank_mask:0xf bound_ctrl:1
	v_xor_b32_e32 v200, v83, v55
	v_xor_b32_e32 v201, v83, v95
	v_xor_b32_e32 v202, v83, v94
	v_xor_b32_e32 v203, v83, v54
	v_add_f32_dpp v204, v55, v200 quad_perm:[2,3,0,1] row_mask:0xf bank_mask:0xf bound_ctrl:1
	v_add_f32_dpp v205, v95, v201 quad_perm:[2,3,0,1] row_mask:0xf bank_mask:0xf bound_ctrl:1
	v_add_f32_dpp v206, v94, v202 quad_perm:[2,3,0,1] row_mask:0xf bank_mask:0xf bound_ctrl:1
	v_add_f32_dpp v207, v54, v203 quad_perm:[2,3,0,1] row_mask:0xf bank_mask:0xf bound_ctrl:1
	v_xor_b32_e32 v200, v84, v204
	v_xor_b32_e32 v201, v84, v205
	v_xor_b32_e32 v202, v84, v206
	v_xor_b32_e32 v203, v84, v207
	v_add_f32_dpp v55, v204, v200 row_shl:4 row_mask:0xf bank_mask:0x5
	v_add_f32_dpp v95, v205, v201 row_shl:4 row_mask:0xf bank_mask:0x5
	v_add_f32_dpp v94, v206, v202 row_shl:4 row_mask:0xf bank_mask:0x5
	v_add_f32_dpp v96, v207, v203 row_shl:4 row_mask:0xf bank_mask:0x5
	v_add_f32_dpp v55, v204, v200 row_shr:4 row_mask:0xf bank_mask:0xa
	v_add_f32_dpp v95, v205, v201 row_shr:4 row_mask:0xf bank_mask:0xa
	v_add_f32_dpp v94, v206, v202 row_shr:4 row_mask:0xf bank_mask:0xa
	v_add_f32_dpp v96, v207, v203 row_shr:4 row_mask:0xf bank_mask:0xa
	v_max_f32_e64 v54, |v55|, |v95|
	v_max_f32_e64 v98, |v94|, |v96|
	v_max3_f32 v97, v97, v54, v98
	v_cvt_pk_bf16_f32 v54, v55, v95
	v_cvt_pk_bf16_f32 v55, v94, v96
	v_lshlrev_b32_e32 v94, 16, v52
	v_and_b32_e32 v52, 0xffff0000, v52
	v_lshlrev_b32_e32 v95, 16, v53
	v_and_b32_e32 v53, 0xffff0000, v53
	v_add_f32_e32 v96, v94, v52
	v_sub_f32_e32 v52, v94, v52
	v_add_f32_e32 v94, v95, v53
	v_sub_f32_e32 v53, v95, v53
	v_add_f32_e32 v95, v96, v94
	v_sub_f32_e32 v94, v96, v94
	v_add_f32_e32 v98, v52, v53
	v_sub_f32_e32 v52, v52, v53
	v_xor_b32_e32 v53, v82, v95
	v_xor_b32_e32 v96, v82, v94
	s_nop 0
	v_add_f32_dpp v53, v95, v53 quad_perm:[1,0,3,2] row_mask:0xf bank_mask:0xf bound_ctrl:1
	v_xor_b32_e32 v95, v82, v98
	v_add_f32_dpp v94, v94, v96 quad_perm:[1,0,3,2] row_mask:0xf bank_mask:0xf bound_ctrl:1
	v_xor_b32_e32 v96, v82, v52
	v_add_f32_dpp v95, v98, v95 quad_perm:[1,0,3,2] row_mask:0xf bank_mask:0xf bound_ctrl:1
	s_nop 0
	v_add_f32_dpp v52, v52, v96 quad_perm:[1,0,3,2] row_mask:0xf bank_mask:0xf bound_ctrl:1
	v_xor_b32_e32 v200, v83, v53
	v_xor_b32_e32 v201, v83, v95
	v_xor_b32_e32 v202, v83, v94
	v_xor_b32_e32 v203, v83, v52
	v_add_f32_dpp v204, v53, v200 quad_perm:[2,3,0,1] row_mask:0xf bank_mask:0xf bound_ctrl:1
	v_add_f32_dpp v205, v95, v201 quad_perm:[2,3,0,1] row_mask:0xf bank_mask:0xf bound_ctrl:1
	v_add_f32_dpp v206, v94, v202 quad_perm:[2,3,0,1] row_mask:0xf bank_mask:0xf bound_ctrl:1
	v_add_f32_dpp v207, v52, v203 quad_perm:[2,3,0,1] row_mask:0xf bank_mask:0xf bound_ctrl:1
	v_xor_b32_e32 v200, v84, v204
	v_xor_b32_e32 v201, v84, v205
	v_xor_b32_e32 v202, v84, v206
	v_xor_b32_e32 v203, v84, v207
	v_add_f32_dpp v53, v204, v200 row_shl:4 row_mask:0xf bank_mask:0x5
	v_add_f32_dpp v95, v205, v201 row_shl:4 row_mask:0xf bank_mask:0x5
	v_add_f32_dpp v94, v206, v202 row_shl:4 row_mask:0xf bank_mask:0x5
	v_add_f32_dpp v96, v207, v203 row_shl:4 row_mask:0xf bank_mask:0x5
	v_add_f32_dpp v53, v204, v200 row_shr:4 row_mask:0xf bank_mask:0xa
	v_add_f32_dpp v95, v205, v201 row_shr:4 row_mask:0xf bank_mask:0xa
	v_add_f32_dpp v94, v206, v202 row_shr:4 row_mask:0xf bank_mask:0xa
	v_add_f32_dpp v96, v207, v203 row_shr:4 row_mask:0xf bank_mask:0xa
	v_max_f32_e64 v52, |v53|, |v95|
	v_max_f32_e64 v98, |v94|, |v96|
	v_max3_f32 v97, v97, v52, v98
	v_cvt_pk_bf16_f32 v52, v53, v95
	v_cvt_pk_bf16_f32 v53, v94, v96
	v_lshlrev_b32_e32 v94, 16, v50
	v_and_b32_e32 v50, 0xffff0000, v50
	v_lshlrev_b32_e32 v95, 16, v51
	v_and_b32_e32 v51, 0xffff0000, v51
	v_add_f32_e32 v96, v94, v50
	v_sub_f32_e32 v50, v94, v50
	v_add_f32_e32 v94, v95, v51
	v_sub_f32_e32 v51, v95, v51
	v_add_f32_e32 v95, v96, v94
	v_sub_f32_e32 v94, v96, v94
	v_add_f32_e32 v98, v50, v51
	v_sub_f32_e32 v50, v50, v51
	v_xor_b32_e32 v51, v82, v95
	v_xor_b32_e32 v96, v82, v94
	s_nop 0
	v_add_f32_dpp v51, v95, v51 quad_perm:[1,0,3,2] row_mask:0xf bank_mask:0xf bound_ctrl:1
	v_xor_b32_e32 v95, v82, v98
	v_add_f32_dpp v94, v94, v96 quad_perm:[1,0,3,2] row_mask:0xf bank_mask:0xf bound_ctrl:1
	v_xor_b32_e32 v96, v82, v50
	v_add_f32_dpp v95, v98, v95 quad_perm:[1,0,3,2] row_mask:0xf bank_mask:0xf bound_ctrl:1
	s_nop 0
	v_add_f32_dpp v50, v50, v96 quad_perm:[1,0,3,2] row_mask:0xf bank_mask:0xf bound_ctrl:1
	v_xor_b32_e32 v200, v83, v51
	v_xor_b32_e32 v201, v83, v95
	v_xor_b32_e32 v202, v83, v94
	v_xor_b32_e32 v203, v83, v50
	v_add_f32_dpp v204, v51, v200 quad_perm:[2,3,0,1] row_mask:0xf bank_mask:0xf bound_ctrl:1
	v_add_f32_dpp v205, v95, v201 quad_perm:[2,3,0,1] row_mask:0xf bank_mask:0xf bound_ctrl:1
	v_add_f32_dpp v206, v94, v202 quad_perm:[2,3,0,1] row_mask:0xf bank_mask:0xf bound_ctrl:1
	v_add_f32_dpp v207, v50, v203 quad_perm:[2,3,0,1] row_mask:0xf bank_mask:0xf bound_ctrl:1
	v_xor_b32_e32 v200, v84, v204
	v_xor_b32_e32 v201, v84, v205
	v_xor_b32_e32 v202, v84, v206
	v_xor_b32_e32 v203, v84, v207
	v_add_f32_dpp v51, v204, v200 row_shl:4 row_mask:0xf bank_mask:0x5
	v_add_f32_dpp v95, v205, v201 row_shl:4 row_mask:0xf bank_mask:0x5
	v_add_f32_dpp v94, v206, v202 row_shl:4 row_mask:0xf bank_mask:0x5
	v_add_f32_dpp v96, v207, v203 row_shl:4 row_mask:0xf bank_mask:0x5
	v_add_f32_dpp v51, v204, v200 row_shr:4 row_mask:0xf bank_mask:0xa
	v_add_f32_dpp v95, v205, v201 row_shr:4 row_mask:0xf bank_mask:0xa
	v_add_f32_dpp v94, v206, v202 row_shr:4 row_mask:0xf bank_mask:0xa
	v_add_f32_dpp v96, v207, v203 row_shr:4 row_mask:0xf bank_mask:0xa
	v_max_f32_e64 v50, |v51|, |v95|
	v_max_f32_e64 v98, |v94|, |v96|
	v_max3_f32 v97, v97, v50, v98
	v_cvt_pk_bf16_f32 v50, v51, v95
	v_cvt_pk_bf16_f32 v51, v94, v96
	v_lshlrev_b32_e32 v94, 16, v48
	v_and_b32_e32 v48, 0xffff0000, v48
	v_lshlrev_b32_e32 v95, 16, v49
	v_and_b32_e32 v49, 0xffff0000, v49
	v_add_f32_e32 v96, v94, v48
	v_sub_f32_e32 v48, v94, v48
	v_add_f32_e32 v94, v95, v49
	v_sub_f32_e32 v49, v95, v49
	v_add_f32_e32 v95, v96, v94
	v_sub_f32_e32 v94, v96, v94
	v_add_f32_e32 v98, v48, v49
	v_sub_f32_e32 v48, v48, v49
	v_xor_b32_e32 v49, v82, v95
	v_xor_b32_e32 v96, v82, v94
	s_nop 0
	v_add_f32_dpp v49, v95, v49 quad_perm:[1,0,3,2] row_mask:0xf bank_mask:0xf bound_ctrl:1
	v_xor_b32_e32 v95, v82, v98
	v_add_f32_dpp v94, v94, v96 quad_perm:[1,0,3,2] row_mask:0xf bank_mask:0xf bound_ctrl:1
	v_xor_b32_e32 v96, v82, v48
	v_add_f32_dpp v95, v98, v95 quad_perm:[1,0,3,2] row_mask:0xf bank_mask:0xf bound_ctrl:1
	s_nop 0
	v_add_f32_dpp v48, v48, v96 quad_perm:[1,0,3,2] row_mask:0xf bank_mask:0xf bound_ctrl:1
	v_xor_b32_e32 v200, v83, v49
	v_xor_b32_e32 v201, v83, v95
	v_xor_b32_e32 v202, v83, v94
	v_xor_b32_e32 v203, v83, v48
	v_add_f32_dpp v204, v49, v200 quad_perm:[2,3,0,1] row_mask:0xf bank_mask:0xf bound_ctrl:1
	v_add_f32_dpp v205, v95, v201 quad_perm:[2,3,0,1] row_mask:0xf bank_mask:0xf bound_ctrl:1
	v_add_f32_dpp v206, v94, v202 quad_perm:[2,3,0,1] row_mask:0xf bank_mask:0xf bound_ctrl:1
	v_add_f32_dpp v207, v48, v203 quad_perm:[2,3,0,1] row_mask:0xf bank_mask:0xf bound_ctrl:1
	v_xor_b32_e32 v200, v84, v204
	v_xor_b32_e32 v201, v84, v205
	v_xor_b32_e32 v202, v84, v206
	v_xor_b32_e32 v203, v84, v207
	v_add_f32_dpp v49, v204, v200 row_shl:4 row_mask:0xf bank_mask:0x5
	v_add_f32_dpp v95, v205, v201 row_shl:4 row_mask:0xf bank_mask:0x5
	v_add_f32_dpp v94, v206, v202 row_shl:4 row_mask:0xf bank_mask:0x5
	v_add_f32_dpp v96, v207, v203 row_shl:4 row_mask:0xf bank_mask:0x5
	v_add_f32_dpp v49, v204, v200 row_shr:4 row_mask:0xf bank_mask:0xa
	v_add_f32_dpp v95, v205, v201 row_shr:4 row_mask:0xf bank_mask:0xa
	v_add_f32_dpp v94, v206, v202 row_shr:4 row_mask:0xf bank_mask:0xa
	v_add_f32_dpp v96, v207, v203 row_shr:4 row_mask:0xf bank_mask:0xa
	v_max_f32_e64 v48, |v49|, |v95|
	v_max_f32_e64 v98, |v94|, |v96|
	v_max3_f32 v97, v97, v48, v98
	v_cvt_pk_bf16_f32 v48, v49, v95
	v_cvt_pk_bf16_f32 v49, v94, v96
	v_lshlrev_b32_e32 v94, 16, v46
	v_and_b32_e32 v46, 0xffff0000, v46
	v_lshlrev_b32_e32 v95, 16, v47
	v_and_b32_e32 v47, 0xffff0000, v47
	v_add_f32_e32 v96, v94, v46
	v_sub_f32_e32 v46, v94, v46
	v_add_f32_e32 v94, v95, v47
	v_sub_f32_e32 v47, v95, v47
	v_add_f32_e32 v95, v96, v94
	v_sub_f32_e32 v94, v96, v94
	v_add_f32_e32 v98, v46, v47
	v_sub_f32_e32 v46, v46, v47
	v_xor_b32_e32 v47, v82, v95
	v_xor_b32_e32 v96, v82, v94
	s_nop 0
	v_add_f32_dpp v47, v95, v47 quad_perm:[1,0,3,2] row_mask:0xf bank_mask:0xf bound_ctrl:1
	v_xor_b32_e32 v95, v82, v98
	v_add_f32_dpp v94, v94, v96 quad_perm:[1,0,3,2] row_mask:0xf bank_mask:0xf bound_ctrl:1
	v_xor_b32_e32 v96, v82, v46
	v_add_f32_dpp v95, v98, v95 quad_perm:[1,0,3,2] row_mask:0xf bank_mask:0xf bound_ctrl:1
	s_nop 0
	v_add_f32_dpp v46, v46, v96 quad_perm:[1,0,3,2] row_mask:0xf bank_mask:0xf bound_ctrl:1
	v_xor_b32_e32 v200, v83, v47
	v_xor_b32_e32 v201, v83, v95
	v_xor_b32_e32 v202, v83, v94
	v_xor_b32_e32 v203, v83, v46
	v_add_f32_dpp v204, v47, v200 quad_perm:[2,3,0,1] row_mask:0xf bank_mask:0xf bound_ctrl:1
	v_add_f32_dpp v205, v95, v201 quad_perm:[2,3,0,1] row_mask:0xf bank_mask:0xf bound_ctrl:1
	v_add_f32_dpp v206, v94, v202 quad_perm:[2,3,0,1] row_mask:0xf bank_mask:0xf bound_ctrl:1
	v_add_f32_dpp v207, v46, v203 quad_perm:[2,3,0,1] row_mask:0xf bank_mask:0xf bound_ctrl:1
	v_xor_b32_e32 v200, v84, v204
	v_xor_b32_e32 v201, v84, v205
	v_xor_b32_e32 v202, v84, v206
	v_xor_b32_e32 v203, v84, v207
	v_add_f32_dpp v47, v204, v200 row_shl:4 row_mask:0xf bank_mask:0x5
	v_add_f32_dpp v95, v205, v201 row_shl:4 row_mask:0xf bank_mask:0x5
	v_add_f32_dpp v94, v206, v202 row_shl:4 row_mask:0xf bank_mask:0x5
	v_add_f32_dpp v96, v207, v203 row_shl:4 row_mask:0xf bank_mask:0x5
	v_add_f32_dpp v47, v204, v200 row_shr:4 row_mask:0xf bank_mask:0xa
	v_add_f32_dpp v95, v205, v201 row_shr:4 row_mask:0xf bank_mask:0xa
	v_add_f32_dpp v94, v206, v202 row_shr:4 row_mask:0xf bank_mask:0xa
	v_add_f32_dpp v96, v207, v203 row_shr:4 row_mask:0xf bank_mask:0xa
	v_max_f32_e64 v46, |v47|, |v95|
	v_max_f32_e64 v98, |v94|, |v96|
	v_max3_f32 v97, v97, v46, v98
	v_cvt_pk_bf16_f32 v46, v47, v95
	v_cvt_pk_bf16_f32 v47, v94, v96
	v_lshlrev_b32_e32 v94, 16, v44
	v_and_b32_e32 v44, 0xffff0000, v44
	v_lshlrev_b32_e32 v95, 16, v45
	v_and_b32_e32 v45, 0xffff0000, v45
	v_add_f32_e32 v96, v94, v44
	v_sub_f32_e32 v44, v94, v44
	v_add_f32_e32 v94, v95, v45
	v_sub_f32_e32 v45, v95, v45
	v_add_f32_e32 v95, v96, v94
	v_sub_f32_e32 v94, v96, v94
	v_add_f32_e32 v98, v44, v45
	v_sub_f32_e32 v44, v44, v45
	v_xor_b32_e32 v45, v82, v95
	v_xor_b32_e32 v96, v82, v94
	s_nop 0
	v_add_f32_dpp v45, v95, v45 quad_perm:[1,0,3,2] row_mask:0xf bank_mask:0xf bound_ctrl:1
	v_xor_b32_e32 v95, v82, v98
	v_add_f32_dpp v94, v94, v96 quad_perm:[1,0,3,2] row_mask:0xf bank_mask:0xf bound_ctrl:1
	v_xor_b32_e32 v96, v82, v44
	v_add_f32_dpp v95, v98, v95 quad_perm:[1,0,3,2] row_mask:0xf bank_mask:0xf bound_ctrl:1
	s_nop 0
	v_add_f32_dpp v44, v44, v96 quad_perm:[1,0,3,2] row_mask:0xf bank_mask:0xf bound_ctrl:1
	v_xor_b32_e32 v200, v83, v45
	v_xor_b32_e32 v201, v83, v95
	v_xor_b32_e32 v202, v83, v94
	v_xor_b32_e32 v203, v83, v44
	v_add_f32_dpp v204, v45, v200 quad_perm:[2,3,0,1] row_mask:0xf bank_mask:0xf bound_ctrl:1
	v_add_f32_dpp v205, v95, v201 quad_perm:[2,3,0,1] row_mask:0xf bank_mask:0xf bound_ctrl:1
	v_add_f32_dpp v206, v94, v202 quad_perm:[2,3,0,1] row_mask:0xf bank_mask:0xf bound_ctrl:1
	v_add_f32_dpp v207, v44, v203 quad_perm:[2,3,0,1] row_mask:0xf bank_mask:0xf bound_ctrl:1
	v_xor_b32_e32 v200, v84, v204
	v_xor_b32_e32 v201, v84, v205
	v_xor_b32_e32 v202, v84, v206
	v_xor_b32_e32 v203, v84, v207
	v_add_f32_dpp v45, v204, v200 row_shl:4 row_mask:0xf bank_mask:0x5
	v_add_f32_dpp v95, v205, v201 row_shl:4 row_mask:0xf bank_mask:0x5
	v_add_f32_dpp v94, v206, v202 row_shl:4 row_mask:0xf bank_mask:0x5
	v_add_f32_dpp v96, v207, v203 row_shl:4 row_mask:0xf bank_mask:0x5
	v_add_f32_dpp v45, v204, v200 row_shr:4 row_mask:0xf bank_mask:0xa
	v_add_f32_dpp v95, v205, v201 row_shr:4 row_mask:0xf bank_mask:0xa
	v_add_f32_dpp v94, v206, v202 row_shr:4 row_mask:0xf bank_mask:0xa
	v_add_f32_dpp v96, v207, v203 row_shr:4 row_mask:0xf bank_mask:0xa
	v_max_f32_e64 v44, |v45|, |v95|
	v_max_f32_e64 v98, |v94|, |v96|
	v_max3_f32 v97, v97, v44, v98
	v_cvt_pk_bf16_f32 v44, v45, v95
	v_cvt_pk_bf16_f32 v45, v94, v96
	v_lshlrev_b32_e32 v94, 16, v42
	v_and_b32_e32 v42, 0xffff0000, v42
	v_lshlrev_b32_e32 v95, 16, v43
	v_and_b32_e32 v43, 0xffff0000, v43
	v_add_f32_e32 v96, v94, v42
	v_sub_f32_e32 v42, v94, v42
	v_add_f32_e32 v94, v95, v43
	v_sub_f32_e32 v43, v95, v43
	v_add_f32_e32 v95, v96, v94
	v_sub_f32_e32 v94, v96, v94
	v_add_f32_e32 v98, v42, v43
	v_sub_f32_e32 v42, v42, v43
	v_xor_b32_e32 v43, v82, v95
	v_xor_b32_e32 v96, v82, v94
	s_nop 0
	v_add_f32_dpp v43, v95, v43 quad_perm:[1,0,3,2] row_mask:0xf bank_mask:0xf bound_ctrl:1
	v_xor_b32_e32 v95, v82, v98
	v_add_f32_dpp v94, v94, v96 quad_perm:[1,0,3,2] row_mask:0xf bank_mask:0xf bound_ctrl:1
	v_xor_b32_e32 v96, v82, v42
	v_add_f32_dpp v95, v98, v95 quad_perm:[1,0,3,2] row_mask:0xf bank_mask:0xf bound_ctrl:1
	s_nop 0
	v_add_f32_dpp v42, v42, v96 quad_perm:[1,0,3,2] row_mask:0xf bank_mask:0xf bound_ctrl:1
	v_xor_b32_e32 v200, v83, v43
	v_xor_b32_e32 v201, v83, v95
	v_xor_b32_e32 v202, v83, v94
	v_xor_b32_e32 v203, v83, v42
	v_add_f32_dpp v204, v43, v200 quad_perm:[2,3,0,1] row_mask:0xf bank_mask:0xf bound_ctrl:1
	v_add_f32_dpp v205, v95, v201 quad_perm:[2,3,0,1] row_mask:0xf bank_mask:0xf bound_ctrl:1
	v_add_f32_dpp v206, v94, v202 quad_perm:[2,3,0,1] row_mask:0xf bank_mask:0xf bound_ctrl:1
	v_add_f32_dpp v207, v42, v203 quad_perm:[2,3,0,1] row_mask:0xf bank_mask:0xf bound_ctrl:1
	v_xor_b32_e32 v200, v84, v204
	v_xor_b32_e32 v201, v84, v205
	v_xor_b32_e32 v202, v84, v206
	v_xor_b32_e32 v203, v84, v207
	v_add_f32_dpp v43, v204, v200 row_shl:4 row_mask:0xf bank_mask:0x5
	v_add_f32_dpp v95, v205, v201 row_shl:4 row_mask:0xf bank_mask:0x5
	v_add_f32_dpp v94, v206, v202 row_shl:4 row_mask:0xf bank_mask:0x5
	v_add_f32_dpp v96, v207, v203 row_shl:4 row_mask:0xf bank_mask:0x5
	v_add_f32_dpp v43, v204, v200 row_shr:4 row_mask:0xf bank_mask:0xa
	v_add_f32_dpp v95, v205, v201 row_shr:4 row_mask:0xf bank_mask:0xa
	v_add_f32_dpp v94, v206, v202 row_shr:4 row_mask:0xf bank_mask:0xa
	v_add_f32_dpp v96, v207, v203 row_shr:4 row_mask:0xf bank_mask:0xa
	v_max_f32_e64 v42, |v43|, |v95|
	v_max_f32_e64 v98, |v94|, |v96|
	v_max3_f32 v97, v97, v42, v98
	v_cvt_pk_bf16_f32 v42, v43, v95
	v_cvt_pk_bf16_f32 v43, v94, v96
	v_lshlrev_b32_e32 v94, 16, v40
	v_and_b32_e32 v40, 0xffff0000, v40
	v_lshlrev_b32_e32 v95, 16, v41
	v_and_b32_e32 v41, 0xffff0000, v41
	v_add_f32_e32 v96, v94, v40
	v_sub_f32_e32 v40, v94, v40
	v_add_f32_e32 v94, v95, v41
	v_sub_f32_e32 v41, v95, v41
	v_add_f32_e32 v95, v96, v94
	v_sub_f32_e32 v94, v96, v94
	v_add_f32_e32 v98, v40, v41
	v_sub_f32_e32 v40, v40, v41
	v_xor_b32_e32 v41, v82, v95
	v_xor_b32_e32 v96, v82, v94
	s_nop 0
	v_add_f32_dpp v41, v95, v41 quad_perm:[1,0,3,2] row_mask:0xf bank_mask:0xf bound_ctrl:1
	v_xor_b32_e32 v95, v82, v98
	v_add_f32_dpp v94, v94, v96 quad_perm:[1,0,3,2] row_mask:0xf bank_mask:0xf bound_ctrl:1
	v_xor_b32_e32 v96, v82, v40
	v_add_f32_dpp v95, v98, v95 quad_perm:[1,0,3,2] row_mask:0xf bank_mask:0xf bound_ctrl:1
	s_nop 0
	v_add_f32_dpp v40, v40, v96 quad_perm:[1,0,3,2] row_mask:0xf bank_mask:0xf bound_ctrl:1
	v_xor_b32_e32 v200, v83, v41
	v_xor_b32_e32 v201, v83, v95
	v_xor_b32_e32 v202, v83, v94
	v_xor_b32_e32 v203, v83, v40
	v_add_f32_dpp v204, v41, v200 quad_perm:[2,3,0,1] row_mask:0xf bank_mask:0xf bound_ctrl:1
	v_add_f32_dpp v205, v95, v201 quad_perm:[2,3,0,1] row_mask:0xf bank_mask:0xf bound_ctrl:1
	v_add_f32_dpp v206, v94, v202 quad_perm:[2,3,0,1] row_mask:0xf bank_mask:0xf bound_ctrl:1
	v_add_f32_dpp v207, v40, v203 quad_perm:[2,3,0,1] row_mask:0xf bank_mask:0xf bound_ctrl:1
	v_xor_b32_e32 v200, v84, v204
	v_xor_b32_e32 v201, v84, v205
	v_xor_b32_e32 v202, v84, v206
	v_xor_b32_e32 v203, v84, v207
	v_add_f32_dpp v41, v204, v200 row_shl:4 row_mask:0xf bank_mask:0x5
	v_add_f32_dpp v95, v205, v201 row_shl:4 row_mask:0xf bank_mask:0x5
	v_add_f32_dpp v94, v206, v202 row_shl:4 row_mask:0xf bank_mask:0x5
	v_add_f32_dpp v96, v207, v203 row_shl:4 row_mask:0xf bank_mask:0x5
	v_add_f32_dpp v41, v204, v200 row_shr:4 row_mask:0xf bank_mask:0xa
	v_add_f32_dpp v95, v205, v201 row_shr:4 row_mask:0xf bank_mask:0xa
	v_add_f32_dpp v94, v206, v202 row_shr:4 row_mask:0xf bank_mask:0xa
	v_add_f32_dpp v96, v207, v203 row_shr:4 row_mask:0xf bank_mask:0xa
	v_max_f32_e64 v40, |v41|, |v95|
	v_max_f32_e64 v98, |v94|, |v96|
	v_max3_f32 v97, v97, v40, v98
	v_cvt_pk_bf16_f32 v40, v41, v95
	v_cvt_pk_bf16_f32 v41, v94, v96
	v_lshlrev_b32_e32 v94, 16, v38
	v_and_b32_e32 v38, 0xffff0000, v38
	v_lshlrev_b32_e32 v95, 16, v39
	v_and_b32_e32 v39, 0xffff0000, v39
	v_add_f32_e32 v96, v94, v38
	v_sub_f32_e32 v38, v94, v38
	v_add_f32_e32 v94, v95, v39
	v_sub_f32_e32 v39, v95, v39
	v_add_f32_e32 v95, v96, v94
	v_sub_f32_e32 v94, v96, v94
	v_add_f32_e32 v98, v38, v39
	v_sub_f32_e32 v38, v38, v39
	v_xor_b32_e32 v39, v82, v95
	v_xor_b32_e32 v96, v82, v94
	s_nop 0
	v_add_f32_dpp v39, v95, v39 quad_perm:[1,0,3,2] row_mask:0xf bank_mask:0xf bound_ctrl:1
	v_xor_b32_e32 v95, v82, v98
	v_add_f32_dpp v94, v94, v96 quad_perm:[1,0,3,2] row_mask:0xf bank_mask:0xf bound_ctrl:1
	v_xor_b32_e32 v96, v82, v38
	v_add_f32_dpp v95, v98, v95 quad_perm:[1,0,3,2] row_mask:0xf bank_mask:0xf bound_ctrl:1
	s_nop 0
	v_add_f32_dpp v38, v38, v96 quad_perm:[1,0,3,2] row_mask:0xf bank_mask:0xf bound_ctrl:1
	v_xor_b32_e32 v200, v83, v39
	v_xor_b32_e32 v201, v83, v95
	v_xor_b32_e32 v202, v83, v94
	v_xor_b32_e32 v203, v83, v38
	v_add_f32_dpp v204, v39, v200 quad_perm:[2,3,0,1] row_mask:0xf bank_mask:0xf bound_ctrl:1
	v_add_f32_dpp v205, v95, v201 quad_perm:[2,3,0,1] row_mask:0xf bank_mask:0xf bound_ctrl:1
	v_add_f32_dpp v206, v94, v202 quad_perm:[2,3,0,1] row_mask:0xf bank_mask:0xf bound_ctrl:1
	v_add_f32_dpp v207, v38, v203 quad_perm:[2,3,0,1] row_mask:0xf bank_mask:0xf bound_ctrl:1
	v_xor_b32_e32 v200, v84, v204
	v_xor_b32_e32 v201, v84, v205
	v_xor_b32_e32 v202, v84, v206
	v_xor_b32_e32 v203, v84, v207
	v_add_f32_dpp v39, v204, v200 row_shl:4 row_mask:0xf bank_mask:0x5
	v_add_f32_dpp v95, v205, v201 row_shl:4 row_mask:0xf bank_mask:0x5
	v_add_f32_dpp v94, v206, v202 row_shl:4 row_mask:0xf bank_mask:0x5
	v_add_f32_dpp v96, v207, v203 row_shl:4 row_mask:0xf bank_mask:0x5
	v_add_f32_dpp v39, v204, v200 row_shr:4 row_mask:0xf bank_mask:0xa
	v_add_f32_dpp v95, v205, v201 row_shr:4 row_mask:0xf bank_mask:0xa
	v_add_f32_dpp v94, v206, v202 row_shr:4 row_mask:0xf bank_mask:0xa
	v_add_f32_dpp v96, v207, v203 row_shr:4 row_mask:0xf bank_mask:0xa
	v_max_f32_e64 v38, |v39|, |v95|
	v_max_f32_e64 v98, |v94|, |v96|
	v_max3_f32 v97, v97, v38, v98
	v_cvt_pk_bf16_f32 v38, v39, v95
	v_cvt_pk_bf16_f32 v39, v94, v96
	v_lshlrev_b32_e32 v94, 16, v36
	v_and_b32_e32 v36, 0xffff0000, v36
	v_lshlrev_b32_e32 v95, 16, v37
	v_and_b32_e32 v37, 0xffff0000, v37
	v_add_f32_e32 v96, v94, v36
	v_sub_f32_e32 v36, v94, v36
	v_add_f32_e32 v94, v95, v37
	v_sub_f32_e32 v37, v95, v37
	v_add_f32_e32 v95, v96, v94
	v_sub_f32_e32 v94, v96, v94
	v_add_f32_e32 v98, v36, v37
	v_sub_f32_e32 v36, v36, v37
	v_xor_b32_e32 v37, v82, v95
	v_xor_b32_e32 v96, v82, v94
	s_nop 0
	v_add_f32_dpp v37, v95, v37 quad_perm:[1,0,3,2] row_mask:0xf bank_mask:0xf bound_ctrl:1
	v_xor_b32_e32 v95, v82, v98
	v_add_f32_dpp v94, v94, v96 quad_perm:[1,0,3,2] row_mask:0xf bank_mask:0xf bound_ctrl:1
	v_xor_b32_e32 v96, v82, v36
	v_add_f32_dpp v95, v98, v95 quad_perm:[1,0,3,2] row_mask:0xf bank_mask:0xf bound_ctrl:1
	s_nop 0
	v_add_f32_dpp v36, v36, v96 quad_perm:[1,0,3,2] row_mask:0xf bank_mask:0xf bound_ctrl:1
	v_xor_b32_e32 v200, v83, v37
	v_xor_b32_e32 v201, v83, v95
	v_xor_b32_e32 v202, v83, v94
	v_xor_b32_e32 v203, v83, v36
	v_add_f32_dpp v204, v37, v200 quad_perm:[2,3,0,1] row_mask:0xf bank_mask:0xf bound_ctrl:1
	v_add_f32_dpp v205, v95, v201 quad_perm:[2,3,0,1] row_mask:0xf bank_mask:0xf bound_ctrl:1
	v_add_f32_dpp v206, v94, v202 quad_perm:[2,3,0,1] row_mask:0xf bank_mask:0xf bound_ctrl:1
	v_add_f32_dpp v207, v36, v203 quad_perm:[2,3,0,1] row_mask:0xf bank_mask:0xf bound_ctrl:1
	v_xor_b32_e32 v200, v84, v204
	v_xor_b32_e32 v201, v84, v205
	v_xor_b32_e32 v202, v84, v206
	v_xor_b32_e32 v203, v84, v207
	v_add_f32_dpp v37, v204, v200 row_shl:4 row_mask:0xf bank_mask:0x5
	v_add_f32_dpp v95, v205, v201 row_shl:4 row_mask:0xf bank_mask:0x5
	v_add_f32_dpp v94, v206, v202 row_shl:4 row_mask:0xf bank_mask:0x5
	v_add_f32_dpp v96, v207, v203 row_shl:4 row_mask:0xf bank_mask:0x5
	v_add_f32_dpp v37, v204, v200 row_shr:4 row_mask:0xf bank_mask:0xa
	v_add_f32_dpp v95, v205, v201 row_shr:4 row_mask:0xf bank_mask:0xa
	v_add_f32_dpp v94, v206, v202 row_shr:4 row_mask:0xf bank_mask:0xa
	v_add_f32_dpp v96, v207, v203 row_shr:4 row_mask:0xf bank_mask:0xa
	v_max_f32_e64 v36, |v37|, |v95|
	v_max_f32_e64 v98, |v94|, |v96|
	v_max3_f32 v97, v97, v36, v98
	v_cvt_pk_bf16_f32 v36, v37, v95
	v_cvt_pk_bf16_f32 v37, v94, v96
	v_lshlrev_b32_e32 v94, 16, v34
	v_and_b32_e32 v34, 0xffff0000, v34
	v_lshlrev_b32_e32 v95, 16, v35
	v_and_b32_e32 v35, 0xffff0000, v35
	v_add_f32_e32 v96, v94, v34
	v_sub_f32_e32 v34, v94, v34
	v_add_f32_e32 v94, v95, v35
	v_sub_f32_e32 v35, v95, v35
	v_add_f32_e32 v95, v96, v94
	v_sub_f32_e32 v94, v96, v94
	v_add_f32_e32 v98, v34, v35
	v_sub_f32_e32 v34, v34, v35
	v_xor_b32_e32 v35, v82, v95
	v_xor_b32_e32 v96, v82, v94
	s_nop 0
	v_add_f32_dpp v35, v95, v35 quad_perm:[1,0,3,2] row_mask:0xf bank_mask:0xf bound_ctrl:1
	v_xor_b32_e32 v95, v82, v98
	v_add_f32_dpp v94, v94, v96 quad_perm:[1,0,3,2] row_mask:0xf bank_mask:0xf bound_ctrl:1
	v_xor_b32_e32 v96, v82, v34
	v_add_f32_dpp v95, v98, v95 quad_perm:[1,0,3,2] row_mask:0xf bank_mask:0xf bound_ctrl:1
	s_nop 0
	v_add_f32_dpp v34, v34, v96 quad_perm:[1,0,3,2] row_mask:0xf bank_mask:0xf bound_ctrl:1
	v_xor_b32_e32 v200, v83, v35
	v_xor_b32_e32 v201, v83, v95
	v_xor_b32_e32 v202, v83, v94
	v_xor_b32_e32 v203, v83, v34
	v_add_f32_dpp v204, v35, v200 quad_perm:[2,3,0,1] row_mask:0xf bank_mask:0xf bound_ctrl:1
	v_add_f32_dpp v205, v95, v201 quad_perm:[2,3,0,1] row_mask:0xf bank_mask:0xf bound_ctrl:1
	v_add_f32_dpp v206, v94, v202 quad_perm:[2,3,0,1] row_mask:0xf bank_mask:0xf bound_ctrl:1
	v_add_f32_dpp v207, v34, v203 quad_perm:[2,3,0,1] row_mask:0xf bank_mask:0xf bound_ctrl:1
	v_xor_b32_e32 v200, v84, v204
	v_xor_b32_e32 v201, v84, v205
	v_xor_b32_e32 v202, v84, v206
	v_xor_b32_e32 v203, v84, v207
	v_add_f32_dpp v35, v204, v200 row_shl:4 row_mask:0xf bank_mask:0x5
	v_add_f32_dpp v95, v205, v201 row_shl:4 row_mask:0xf bank_mask:0x5
	v_add_f32_dpp v94, v206, v202 row_shl:4 row_mask:0xf bank_mask:0x5
	v_add_f32_dpp v96, v207, v203 row_shl:4 row_mask:0xf bank_mask:0x5
	v_add_f32_dpp v35, v204, v200 row_shr:4 row_mask:0xf bank_mask:0xa
	v_add_f32_dpp v95, v205, v201 row_shr:4 row_mask:0xf bank_mask:0xa
	v_add_f32_dpp v94, v206, v202 row_shr:4 row_mask:0xf bank_mask:0xa
	v_add_f32_dpp v96, v207, v203 row_shr:4 row_mask:0xf bank_mask:0xa
	v_max_f32_e64 v34, |v35|, |v95|
	v_max_f32_e64 v98, |v94|, |v96|
	v_max3_f32 v97, v97, v34, v98
	v_cvt_pk_bf16_f32 v34, v35, v95
	v_cvt_pk_bf16_f32 v35, v94, v96
	v_lshlrev_b32_e32 v94, 16, v32
	v_and_b32_e32 v32, 0xffff0000, v32
	v_lshlrev_b32_e32 v95, 16, v33
	v_and_b32_e32 v33, 0xffff0000, v33
	v_add_f32_e32 v96, v94, v32
	v_sub_f32_e32 v32, v94, v32
	v_add_f32_e32 v94, v95, v33
	v_sub_f32_e32 v33, v95, v33
	v_add_f32_e32 v95, v96, v94
	v_sub_f32_e32 v94, v96, v94
	v_add_f32_e32 v98, v32, v33
	v_sub_f32_e32 v32, v32, v33
	v_xor_b32_e32 v33, v82, v95
	v_xor_b32_e32 v96, v82, v94
	s_nop 0
	v_add_f32_dpp v33, v95, v33 quad_perm:[1,0,3,2] row_mask:0xf bank_mask:0xf bound_ctrl:1
	v_xor_b32_e32 v95, v82, v98
	v_add_f32_dpp v94, v94, v96 quad_perm:[1,0,3,2] row_mask:0xf bank_mask:0xf bound_ctrl:1
	v_xor_b32_e32 v96, v82, v32
	v_add_f32_dpp v95, v98, v95 quad_perm:[1,0,3,2] row_mask:0xf bank_mask:0xf bound_ctrl:1
	s_nop 0
	v_add_f32_dpp v32, v32, v96 quad_perm:[1,0,3,2] row_mask:0xf bank_mask:0xf bound_ctrl:1
	v_xor_b32_e32 v200, v83, v33
	v_xor_b32_e32 v201, v83, v95
	v_xor_b32_e32 v202, v83, v94
	v_xor_b32_e32 v203, v83, v32
	v_add_f32_dpp v204, v33, v200 quad_perm:[2,3,0,1] row_mask:0xf bank_mask:0xf bound_ctrl:1
	v_add_f32_dpp v205, v95, v201 quad_perm:[2,3,0,1] row_mask:0xf bank_mask:0xf bound_ctrl:1
	v_add_f32_dpp v206, v94, v202 quad_perm:[2,3,0,1] row_mask:0xf bank_mask:0xf bound_ctrl:1
	v_add_f32_dpp v207, v32, v203 quad_perm:[2,3,0,1] row_mask:0xf bank_mask:0xf bound_ctrl:1
	v_xor_b32_e32 v200, v84, v204
	v_xor_b32_e32 v201, v84, v205
	v_xor_b32_e32 v202, v84, v206
	v_xor_b32_e32 v203, v84, v207
	v_add_f32_dpp v33, v204, v200 row_shl:4 row_mask:0xf bank_mask:0x5
	v_add_f32_dpp v95, v205, v201 row_shl:4 row_mask:0xf bank_mask:0x5
	v_add_f32_dpp v94, v206, v202 row_shl:4 row_mask:0xf bank_mask:0x5
	v_add_f32_dpp v96, v207, v203 row_shl:4 row_mask:0xf bank_mask:0x5
	v_add_f32_dpp v33, v204, v200 row_shr:4 row_mask:0xf bank_mask:0xa
	v_add_f32_dpp v95, v205, v201 row_shr:4 row_mask:0xf bank_mask:0xa
	v_add_f32_dpp v94, v206, v202 row_shr:4 row_mask:0xf bank_mask:0xa
	v_add_f32_dpp v96, v207, v203 row_shr:4 row_mask:0xf bank_mask:0xa
	v_max_f32_e64 v32, |v33|, |v95|
	v_max_f32_e64 v98, |v94|, |v96|
	v_max3_f32 v97, v97, v32, v98
	v_cvt_pk_bf16_f32 v32, v33, v95
	v_cvt_pk_bf16_f32 v33, v94, v96
	v_lshlrev_b32_e32 v94, 16, v30
	v_and_b32_e32 v30, 0xffff0000, v30
	v_lshlrev_b32_e32 v95, 16, v31
	v_and_b32_e32 v31, 0xffff0000, v31
	v_add_f32_e32 v96, v94, v30
	v_sub_f32_e32 v30, v94, v30
	v_add_f32_e32 v94, v95, v31
	v_sub_f32_e32 v31, v95, v31
	v_add_f32_e32 v95, v96, v94
	v_sub_f32_e32 v94, v96, v94
	v_add_f32_e32 v98, v30, v31
	v_sub_f32_e32 v30, v30, v31
	v_xor_b32_e32 v31, v82, v95
	v_xor_b32_e32 v96, v82, v94
	s_nop 0
	v_add_f32_dpp v31, v95, v31 quad_perm:[1,0,3,2] row_mask:0xf bank_mask:0xf bound_ctrl:1
	v_xor_b32_e32 v95, v82, v98
	v_add_f32_dpp v94, v94, v96 quad_perm:[1,0,3,2] row_mask:0xf bank_mask:0xf bound_ctrl:1
	v_xor_b32_e32 v96, v82, v30
	v_add_f32_dpp v95, v98, v95 quad_perm:[1,0,3,2] row_mask:0xf bank_mask:0xf bound_ctrl:1
	s_nop 0
	v_add_f32_dpp v30, v30, v96 quad_perm:[1,0,3,2] row_mask:0xf bank_mask:0xf bound_ctrl:1
	v_xor_b32_e32 v200, v83, v31
	v_xor_b32_e32 v201, v83, v95
	v_xor_b32_e32 v202, v83, v94
	v_xor_b32_e32 v203, v83, v30
	v_add_f32_dpp v204, v31, v200 quad_perm:[2,3,0,1] row_mask:0xf bank_mask:0xf bound_ctrl:1
	v_add_f32_dpp v205, v95, v201 quad_perm:[2,3,0,1] row_mask:0xf bank_mask:0xf bound_ctrl:1
	v_add_f32_dpp v206, v94, v202 quad_perm:[2,3,0,1] row_mask:0xf bank_mask:0xf bound_ctrl:1
	v_add_f32_dpp v207, v30, v203 quad_perm:[2,3,0,1] row_mask:0xf bank_mask:0xf bound_ctrl:1
	v_xor_b32_e32 v200, v84, v204
	v_xor_b32_e32 v201, v84, v205
	v_xor_b32_e32 v202, v84, v206
	v_xor_b32_e32 v203, v84, v207
	v_add_f32_dpp v31, v204, v200 row_shl:4 row_mask:0xf bank_mask:0x5
	v_add_f32_dpp v95, v205, v201 row_shl:4 row_mask:0xf bank_mask:0x5
	v_add_f32_dpp v94, v206, v202 row_shl:4 row_mask:0xf bank_mask:0x5
	v_add_f32_dpp v96, v207, v203 row_shl:4 row_mask:0xf bank_mask:0x5
	v_add_f32_dpp v31, v204, v200 row_shr:4 row_mask:0xf bank_mask:0xa
	v_add_f32_dpp v95, v205, v201 row_shr:4 row_mask:0xf bank_mask:0xa
	v_add_f32_dpp v94, v206, v202 row_shr:4 row_mask:0xf bank_mask:0xa
	v_add_f32_dpp v96, v207, v203 row_shr:4 row_mask:0xf bank_mask:0xa
	v_max_f32_e64 v30, |v31|, |v95|
	v_max_f32_e64 v98, |v94|, |v96|
	v_max3_f32 v97, v97, v30, v98
	v_cvt_pk_bf16_f32 v30, v31, v95
	v_cvt_pk_bf16_f32 v31, v94, v96
	v_lshlrev_b32_e32 v94, 16, v28
	v_and_b32_e32 v28, 0xffff0000, v28
	v_lshlrev_b32_e32 v95, 16, v29
	v_and_b32_e32 v29, 0xffff0000, v29
	v_add_f32_e32 v96, v94, v28
	v_sub_f32_e32 v28, v94, v28
	v_add_f32_e32 v94, v95, v29
	v_sub_f32_e32 v29, v95, v29
	v_add_f32_e32 v95, v96, v94
	v_sub_f32_e32 v94, v96, v94
	v_add_f32_e32 v98, v28, v29
	v_sub_f32_e32 v28, v28, v29
	v_xor_b32_e32 v29, v82, v95
	v_xor_b32_e32 v96, v82, v94
	s_nop 0
	v_add_f32_dpp v29, v95, v29 quad_perm:[1,0,3,2] row_mask:0xf bank_mask:0xf bound_ctrl:1
	v_xor_b32_e32 v95, v82, v98
	v_add_f32_dpp v94, v94, v96 quad_perm:[1,0,3,2] row_mask:0xf bank_mask:0xf bound_ctrl:1
	v_xor_b32_e32 v96, v82, v28
	v_add_f32_dpp v95, v98, v95 quad_perm:[1,0,3,2] row_mask:0xf bank_mask:0xf bound_ctrl:1
	s_nop 0
	v_add_f32_dpp v28, v28, v96 quad_perm:[1,0,3,2] row_mask:0xf bank_mask:0xf bound_ctrl:1
	v_xor_b32_e32 v200, v83, v29
	v_xor_b32_e32 v201, v83, v95
	v_xor_b32_e32 v202, v83, v94
	v_xor_b32_e32 v203, v83, v28
	v_add_f32_dpp v204, v29, v200 quad_perm:[2,3,0,1] row_mask:0xf bank_mask:0xf bound_ctrl:1
	v_add_f32_dpp v205, v95, v201 quad_perm:[2,3,0,1] row_mask:0xf bank_mask:0xf bound_ctrl:1
	v_add_f32_dpp v206, v94, v202 quad_perm:[2,3,0,1] row_mask:0xf bank_mask:0xf bound_ctrl:1
	v_add_f32_dpp v207, v28, v203 quad_perm:[2,3,0,1] row_mask:0xf bank_mask:0xf bound_ctrl:1
	v_xor_b32_e32 v200, v84, v204
	v_xor_b32_e32 v201, v84, v205
	v_xor_b32_e32 v202, v84, v206
	v_xor_b32_e32 v203, v84, v207
	v_add_f32_dpp v29, v204, v200 row_shl:4 row_mask:0xf bank_mask:0x5
	v_add_f32_dpp v95, v205, v201 row_shl:4 row_mask:0xf bank_mask:0x5
	v_add_f32_dpp v94, v206, v202 row_shl:4 row_mask:0xf bank_mask:0x5
	v_add_f32_dpp v96, v207, v203 row_shl:4 row_mask:0xf bank_mask:0x5
	v_add_f32_dpp v29, v204, v200 row_shr:4 row_mask:0xf bank_mask:0xa
	v_add_f32_dpp v95, v205, v201 row_shr:4 row_mask:0xf bank_mask:0xa
	v_add_f32_dpp v94, v206, v202 row_shr:4 row_mask:0xf bank_mask:0xa
	v_add_f32_dpp v96, v207, v203 row_shr:4 row_mask:0xf bank_mask:0xa
	v_max_f32_e64 v28, |v29|, |v95|
	v_max_f32_e64 v98, |v94|, |v96|
	v_max3_f32 v97, v97, v28, v98
	v_cvt_pk_bf16_f32 v28, v29, v95
	v_cvt_pk_bf16_f32 v29, v94, v96
	v_lshlrev_b32_e32 v94, 16, v26
	v_and_b32_e32 v26, 0xffff0000, v26
	v_lshlrev_b32_e32 v95, 16, v27
	v_and_b32_e32 v27, 0xffff0000, v27
	v_add_f32_e32 v96, v94, v26
	v_sub_f32_e32 v26, v94, v26
	v_add_f32_e32 v94, v95, v27
	v_sub_f32_e32 v27, v95, v27
	v_add_f32_e32 v95, v96, v94
	v_sub_f32_e32 v94, v96, v94
	v_add_f32_e32 v98, v26, v27
	v_sub_f32_e32 v26, v26, v27
	v_xor_b32_e32 v27, v82, v95
	v_xor_b32_e32 v96, v82, v94
	s_nop 0
	v_add_f32_dpp v27, v95, v27 quad_perm:[1,0,3,2] row_mask:0xf bank_mask:0xf bound_ctrl:1
	v_xor_b32_e32 v95, v82, v98
	v_add_f32_dpp v94, v94, v96 quad_perm:[1,0,3,2] row_mask:0xf bank_mask:0xf bound_ctrl:1
	v_xor_b32_e32 v96, v82, v26
	v_add_f32_dpp v95, v98, v95 quad_perm:[1,0,3,2] row_mask:0xf bank_mask:0xf bound_ctrl:1
	s_nop 0
	v_add_f32_dpp v26, v26, v96 quad_perm:[1,0,3,2] row_mask:0xf bank_mask:0xf bound_ctrl:1
	v_xor_b32_e32 v200, v83, v27
	v_xor_b32_e32 v201, v83, v95
	v_xor_b32_e32 v202, v83, v94
	v_xor_b32_e32 v203, v83, v26
	v_add_f32_dpp v204, v27, v200 quad_perm:[2,3,0,1] row_mask:0xf bank_mask:0xf bound_ctrl:1
	v_add_f32_dpp v205, v95, v201 quad_perm:[2,3,0,1] row_mask:0xf bank_mask:0xf bound_ctrl:1
	v_add_f32_dpp v206, v94, v202 quad_perm:[2,3,0,1] row_mask:0xf bank_mask:0xf bound_ctrl:1
	v_add_f32_dpp v207, v26, v203 quad_perm:[2,3,0,1] row_mask:0xf bank_mask:0xf bound_ctrl:1
	v_xor_b32_e32 v200, v84, v204
	v_xor_b32_e32 v201, v84, v205
	v_xor_b32_e32 v202, v84, v206
	v_xor_b32_e32 v203, v84, v207
	v_add_f32_dpp v27, v204, v200 row_shl:4 row_mask:0xf bank_mask:0x5
	v_add_f32_dpp v95, v205, v201 row_shl:4 row_mask:0xf bank_mask:0x5
	v_add_f32_dpp v94, v206, v202 row_shl:4 row_mask:0xf bank_mask:0x5
	v_add_f32_dpp v96, v207, v203 row_shl:4 row_mask:0xf bank_mask:0x5
	v_add_f32_dpp v27, v204, v200 row_shr:4 row_mask:0xf bank_mask:0xa
	v_add_f32_dpp v95, v205, v201 row_shr:4 row_mask:0xf bank_mask:0xa
	v_add_f32_dpp v94, v206, v202 row_shr:4 row_mask:0xf bank_mask:0xa
	v_add_f32_dpp v96, v207, v203 row_shr:4 row_mask:0xf bank_mask:0xa
	v_max_f32_e64 v26, |v27|, |v95|
	v_max_f32_e64 v98, |v94|, |v96|
	v_max3_f32 v97, v97, v26, v98
	v_cvt_pk_bf16_f32 v26, v27, v95
	v_cvt_pk_bf16_f32 v27, v94, v96
	v_lshlrev_b32_e32 v94, 16, v24
	v_and_b32_e32 v24, 0xffff0000, v24
	v_lshlrev_b32_e32 v95, 16, v25
	v_and_b32_e32 v25, 0xffff0000, v25
	v_add_f32_e32 v96, v94, v24
	v_sub_f32_e32 v24, v94, v24
	v_add_f32_e32 v94, v95, v25
	v_sub_f32_e32 v25, v95, v25
	v_add_f32_e32 v95, v96, v94
	v_sub_f32_e32 v94, v96, v94
	v_add_f32_e32 v98, v24, v25
	v_sub_f32_e32 v24, v24, v25
	v_xor_b32_e32 v25, v82, v95
	v_xor_b32_e32 v96, v82, v94
	s_nop 0
	v_add_f32_dpp v25, v95, v25 quad_perm:[1,0,3,2] row_mask:0xf bank_mask:0xf bound_ctrl:1
	v_xor_b32_e32 v95, v82, v98
	v_add_f32_dpp v94, v94, v96 quad_perm:[1,0,3,2] row_mask:0xf bank_mask:0xf bound_ctrl:1
	v_xor_b32_e32 v96, v82, v24
	v_add_f32_dpp v95, v98, v95 quad_perm:[1,0,3,2] row_mask:0xf bank_mask:0xf bound_ctrl:1
	s_nop 0
	v_add_f32_dpp v24, v24, v96 quad_perm:[1,0,3,2] row_mask:0xf bank_mask:0xf bound_ctrl:1
	v_xor_b32_e32 v200, v83, v25
	v_xor_b32_e32 v201, v83, v95
	v_xor_b32_e32 v202, v83, v94
	v_xor_b32_e32 v203, v83, v24
	v_add_f32_dpp v204, v25, v200 quad_perm:[2,3,0,1] row_mask:0xf bank_mask:0xf bound_ctrl:1
	v_add_f32_dpp v205, v95, v201 quad_perm:[2,3,0,1] row_mask:0xf bank_mask:0xf bound_ctrl:1
	v_add_f32_dpp v206, v94, v202 quad_perm:[2,3,0,1] row_mask:0xf bank_mask:0xf bound_ctrl:1
	v_add_f32_dpp v207, v24, v203 quad_perm:[2,3,0,1] row_mask:0xf bank_mask:0xf bound_ctrl:1
	v_xor_b32_e32 v200, v84, v204
	v_xor_b32_e32 v201, v84, v205
	v_xor_b32_e32 v202, v84, v206
	v_xor_b32_e32 v203, v84, v207
	v_add_f32_dpp v24, v204, v200 row_shl:4 row_mask:0xf bank_mask:0x5
	v_add_f32_dpp v25, v205, v201 row_shl:4 row_mask:0xf bank_mask:0x5
	v_add_f32_dpp v94, v206, v202 row_shl:4 row_mask:0xf bank_mask:0x5
	v_add_f32_dpp v95, v207, v203 row_shl:4 row_mask:0xf bank_mask:0x5
	v_add_f32_dpp v24, v204, v200 row_shr:4 row_mask:0xf bank_mask:0xa
	v_add_f32_dpp v25, v205, v201 row_shr:4 row_mask:0xf bank_mask:0xa
	v_add_f32_dpp v94, v206, v202 row_shr:4 row_mask:0xf bank_mask:0xa
	v_add_f32_dpp v95, v207, v203 row_shr:4 row_mask:0xf bank_mask:0xa
	v_max_f32_e64 v96, |v24|, |v25|
	v_max_f32_e64 v98, |v94|, |v95|
	v_max3_f32 v98, v97, v96, v98
	v_lshlrev_b32_e32 v96, 16, v22
	v_and_b32_e32 v22, 0xffff0000, v22
	v_lshlrev_b32_e32 v97, 16, v23
	v_and_b32_e32 v23, 0xffff0000, v23
	v_add_f32_e32 v99, v96, v22
	v_sub_f32_e32 v22, v96, v22
	v_add_f32_e32 v96, v97, v23
	v_sub_f32_e32 v23, v97, v23
	v_add_f32_e32 v97, v99, v96
	v_sub_f32_e32 v96, v99, v96
	v_add_f32_e32 v100, v22, v23
	v_sub_f32_e32 v22, v22, v23
	v_xor_b32_e32 v23, v82, v97
	v_xor_b32_e32 v99, v82, v96
	v_cvt_pk_bf16_f32 v24, v24, v25
	v_cvt_pk_bf16_f32 v25, v94, v95
	s_nop 0
	v_add_f32_dpp v23, v97, v23 quad_perm:[1,0,3,2] row_mask:0xf bank_mask:0xf bound_ctrl:1
	v_xor_b32_e32 v97, v82, v100
	v_add_f32_dpp v96, v96, v99 quad_perm:[1,0,3,2] row_mask:0xf bank_mask:0xf bound_ctrl:1
	v_xor_b32_e32 v99, v82, v22
	v_add_f32_dpp v97, v100, v97 quad_perm:[1,0,3,2] row_mask:0xf bank_mask:0xf bound_ctrl:1
	s_nop 0
	v_add_f32_dpp v22, v22, v99 quad_perm:[1,0,3,2] row_mask:0xf bank_mask:0xf bound_ctrl:1
	v_xor_b32_e32 v200, v83, v23
	v_xor_b32_e32 v201, v83, v97
	v_xor_b32_e32 v202, v83, v96
	v_xor_b32_e32 v203, v83, v22
	v_add_f32_dpp v204, v23, v200 quad_perm:[2,3,0,1] row_mask:0xf bank_mask:0xf bound_ctrl:1
	v_add_f32_dpp v205, v97, v201 quad_perm:[2,3,0,1] row_mask:0xf bank_mask:0xf bound_ctrl:1
	v_add_f32_dpp v206, v96, v202 quad_perm:[2,3,0,1] row_mask:0xf bank_mask:0xf bound_ctrl:1
	v_add_f32_dpp v207, v22, v203 quad_perm:[2,3,0,1] row_mask:0xf bank_mask:0xf bound_ctrl:1
	v_xor_b32_e32 v200, v84, v204
	v_xor_b32_e32 v201, v84, v205
	v_xor_b32_e32 v202, v84, v206
	v_xor_b32_e32 v203, v84, v207
	v_add_f32_dpp v22, v204, v200 row_shl:4 row_mask:0xf bank_mask:0x5
	v_add_f32_dpp v23, v205, v201 row_shl:4 row_mask:0xf bank_mask:0x5
	v_add_f32_dpp v96, v206, v202 row_shl:4 row_mask:0xf bank_mask:0x5
	v_add_f32_dpp v97, v207, v203 row_shl:4 row_mask:0xf bank_mask:0x5
	v_add_f32_dpp v22, v204, v200 row_shr:4 row_mask:0xf bank_mask:0xa
	v_add_f32_dpp v23, v205, v201 row_shr:4 row_mask:0xf bank_mask:0xa
	v_add_f32_dpp v96, v206, v202 row_shr:4 row_mask:0xf bank_mask:0xa
	v_add_f32_dpp v97, v207, v203 row_shr:4 row_mask:0xf bank_mask:0xa
	v_max_f32_e64 v99, |v22|, |v23|
	v_max_f32_e64 v100, |v96|, |v97|
	v_max3_f32 v98, v98, v99, v100
	v_lshlrev_b32_e32 v99, 16, v20
	v_and_b32_e32 v20, 0xffff0000, v20
	v_lshlrev_b32_e32 v100, 16, v21
	v_and_b32_e32 v21, 0xffff0000, v21
	v_add_f32_e32 v101, v99, v20
	v_sub_f32_e32 v20, v99, v20
	v_add_f32_e32 v99, v100, v21
	v_sub_f32_e32 v21, v100, v21
	v_add_f32_e32 v100, v101, v99
	v_sub_f32_e32 v99, v101, v99
	v_add_f32_e32 v102, v20, v21
	v_sub_f32_e32 v20, v20, v21
	v_xor_b32_e32 v21, v82, v100
	v_xor_b32_e32 v101, v82, v99
	v_cvt_pk_bf16_f32 v22, v22, v23
	v_cvt_pk_bf16_f32 v23, v96, v97
	s_nop 0
	v_add_f32_dpp v21, v100, v21 quad_perm:[1,0,3,2] row_mask:0xf bank_mask:0xf bound_ctrl:1
	v_xor_b32_e32 v100, v82, v102
	v_add_f32_dpp v99, v99, v101 quad_perm:[1,0,3,2] row_mask:0xf bank_mask:0xf bound_ctrl:1
	v_xor_b32_e32 v101, v82, v20
	v_add_f32_dpp v100, v102, v100 quad_perm:[1,0,3,2] row_mask:0xf bank_mask:0xf bound_ctrl:1
	s_nop 0
	v_add_f32_dpp v20, v20, v101 quad_perm:[1,0,3,2] row_mask:0xf bank_mask:0xf bound_ctrl:1
	v_xor_b32_e32 v200, v83, v21
	v_xor_b32_e32 v201, v83, v100
	v_xor_b32_e32 v202, v83, v99
	v_xor_b32_e32 v203, v83, v20
	v_add_f32_dpp v204, v21, v200 quad_perm:[2,3,0,1] row_mask:0xf bank_mask:0xf bound_ctrl:1
	v_add_f32_dpp v205, v100, v201 quad_perm:[2,3,0,1] row_mask:0xf bank_mask:0xf bound_ctrl:1
	v_add_f32_dpp v206, v99, v202 quad_perm:[2,3,0,1] row_mask:0xf bank_mask:0xf bound_ctrl:1
	v_add_f32_dpp v207, v20, v203 quad_perm:[2,3,0,1] row_mask:0xf bank_mask:0xf bound_ctrl:1
	v_xor_b32_e32 v200, v84, v204
	v_xor_b32_e32 v201, v84, v205
	v_xor_b32_e32 v202, v84, v206
	v_xor_b32_e32 v203, v84, v207
	v_add_f32_dpp v21, v204, v200 row_shl:4 row_mask:0xf bank_mask:0x5
	v_add_f32_dpp v100, v205, v201 row_shl:4 row_mask:0xf bank_mask:0x5
	v_add_f32_dpp v99, v206, v202 row_shl:4 row_mask:0xf bank_mask:0x5
	v_add_f32_dpp v20, v207, v203 row_shl:4 row_mask:0xf bank_mask:0x5
	v_add_f32_dpp v21, v204, v200 row_shr:4 row_mask:0xf bank_mask:0xa
	v_add_f32_dpp v100, v205, v201 row_shr:4 row_mask:0xf bank_mask:0xa
	v_add_f32_dpp v99, v206, v202 row_shr:4 row_mask:0xf bank_mask:0xa
	v_add_f32_dpp v20, v207, v203 row_shr:4 row_mask:0xf bank_mask:0xa
	v_cvt_pk_bf16_f32 v96, v21, v100
	v_max_f32_e64 v101, |v21|, |v100|
	v_max_f32_e64 v102, |v99|, |v20|
	v_max3_f32 v98, v98, v101, v102
	v_lshlrev_b32_e32 v101, 16, v18
	v_and_b32_e32 v18, 0xffff0000, v18
	v_lshlrev_b32_e32 v102, 16, v19
	v_and_b32_e32 v19, 0xffff0000, v19
	v_add_f32_e32 v103, v101, v18
	v_sub_f32_e32 v18, v101, v18
	v_add_f32_e32 v101, v102, v19
	v_sub_f32_e32 v19, v102, v19
	v_add_f32_e32 v102, v103, v101
	v_sub_f32_e32 v101, v103, v101
	v_add_f32_e32 v104, v18, v19
	v_sub_f32_e32 v18, v18, v19
	v_xor_b32_e32 v19, v82, v102
	v_xor_b32_e32 v103, v82, v101
	v_cvt_pk_bf16_f32 v97, v99, v20
	s_nop 0
	v_add_f32_dpp v19, v102, v19 quad_perm:[1,0,3,2] row_mask:0xf bank_mask:0xf bound_ctrl:1
	v_xor_b32_e32 v102, v82, v104
	v_add_f32_dpp v101, v101, v103 quad_perm:[1,0,3,2] row_mask:0xf bank_mask:0xf bound_ctrl:1
	v_xor_b32_e32 v103, v82, v18
	v_add_f32_dpp v102, v104, v102 quad_perm:[1,0,3,2] row_mask:0xf bank_mask:0xf bound_ctrl:1
	s_nop 0
	v_add_f32_dpp v18, v18, v103 quad_perm:[1,0,3,2] row_mask:0xf bank_mask:0xf bound_ctrl:1
	v_xor_b32_e32 v200, v83, v19
	v_xor_b32_e32 v201, v83, v102
	v_xor_b32_e32 v202, v83, v101
	v_xor_b32_e32 v203, v83, v18
	v_add_f32_dpp v204, v19, v200 quad_perm:[2,3,0,1] row_mask:0xf bank_mask:0xf bound_ctrl:1
	v_add_f32_dpp v205, v102, v201 quad_perm:[2,3,0,1] row_mask:0xf bank_mask:0xf bound_ctrl:1
	v_add_f32_dpp v206, v101, v202 quad_perm:[2,3,0,1] row_mask:0xf bank_mask:0xf bound_ctrl:1
	v_add_f32_dpp v207, v18, v203 quad_perm:[2,3,0,1] row_mask:0xf bank_mask:0xf bound_ctrl:1
	v_xor_b32_e32 v200, v84, v204
	v_xor_b32_e32 v201, v84, v205
	v_xor_b32_e32 v202, v84, v206
	v_xor_b32_e32 v203, v84, v207
	v_add_f32_dpp v19, v204, v200 row_shl:4 row_mask:0xf bank_mask:0x5
	v_add_f32_dpp v102, v205, v201 row_shl:4 row_mask:0xf bank_mask:0x5
	v_add_f32_dpp v101, v206, v202 row_shl:4 row_mask:0xf bank_mask:0x5
	v_add_f32_dpp v18, v207, v203 row_shl:4 row_mask:0xf bank_mask:0x5
	v_add_f32_dpp v19, v204, v200 row_shr:4 row_mask:0xf bank_mask:0xa
	v_add_f32_dpp v102, v205, v201 row_shr:4 row_mask:0xf bank_mask:0xa
	v_add_f32_dpp v101, v206, v202 row_shr:4 row_mask:0xf bank_mask:0xa
	v_add_f32_dpp v18, v207, v203 row_shr:4 row_mask:0xf bank_mask:0xa
	v_max_f32_e64 v103, |v19|, |v102|
	v_max_f32_e64 v104, |v101|, |v18|
	v_max3_f32 v98, v98, v103, v104
	v_lshlrev_b32_e32 v103, 16, v16
	v_and_b32_e32 v16, 0xffff0000, v16
	v_lshlrev_b32_e32 v104, 16, v17
	v_and_b32_e32 v17, 0xffff0000, v17
	v_add_f32_e32 v105, v103, v16
	v_sub_f32_e32 v16, v103, v16
	v_add_f32_e32 v103, v104, v17
	v_sub_f32_e32 v17, v104, v17
	v_add_f32_e32 v104, v105, v103
	v_sub_f32_e32 v103, v105, v103
	v_add_f32_e32 v106, v16, v17
	v_sub_f32_e32 v16, v16, v17
	v_xor_b32_e32 v17, v82, v104
	v_xor_b32_e32 v105, v82, v103
	v_cvt_pk_bf16_f32 v19, v19, v102
	s_nop 0
	v_add_f32_dpp v17, v104, v17 quad_perm:[1,0,3,2] row_mask:0xf bank_mask:0xf bound_ctrl:1
	v_xor_b32_e32 v104, v82, v106
	v_add_f32_dpp v103, v103, v105 quad_perm:[1,0,3,2] row_mask:0xf bank_mask:0xf bound_ctrl:1
	v_xor_b32_e32 v105, v82, v16
	v_add_f32_dpp v104, v106, v104 quad_perm:[1,0,3,2] row_mask:0xf bank_mask:0xf bound_ctrl:1
	s_nop 0
	v_add_f32_dpp v16, v16, v105 quad_perm:[1,0,3,2] row_mask:0xf bank_mask:0xf bound_ctrl:1
	v_xor_b32_e32 v200, v83, v17
	v_xor_b32_e32 v201, v83, v104
	v_xor_b32_e32 v202, v83, v103
	v_xor_b32_e32 v203, v83, v16
	v_add_f32_dpp v204, v17, v200 quad_perm:[2,3,0,1] row_mask:0xf bank_mask:0xf bound_ctrl:1
	v_add_f32_dpp v205, v104, v201 quad_perm:[2,3,0,1] row_mask:0xf bank_mask:0xf bound_ctrl:1
	v_add_f32_dpp v206, v103, v202 quad_perm:[2,3,0,1] row_mask:0xf bank_mask:0xf bound_ctrl:1
	v_add_f32_dpp v207, v16, v203 quad_perm:[2,3,0,1] row_mask:0xf bank_mask:0xf bound_ctrl:1
	v_xor_b32_e32 v200, v84, v204
	v_xor_b32_e32 v201, v84, v205
	v_xor_b32_e32 v202, v84, v206
	v_xor_b32_e32 v203, v84, v207
	v_add_f32_dpp v17, v204, v200 row_shl:4 row_mask:0xf bank_mask:0x5
	v_add_f32_dpp v104, v205, v201 row_shl:4 row_mask:0xf bank_mask:0x5
	v_add_f32_dpp v103, v206, v202 row_shl:4 row_mask:0xf bank_mask:0x5
	v_add_f32_dpp v16, v207, v203 row_shl:4 row_mask:0xf bank_mask:0x5
	v_add_f32_dpp v17, v204, v200 row_shr:4 row_mask:0xf bank_mask:0xa
	v_add_f32_dpp v104, v205, v201 row_shr:4 row_mask:0xf bank_mask:0xa
	v_add_f32_dpp v103, v206, v202 row_shr:4 row_mask:0xf bank_mask:0xa
	v_add_f32_dpp v16, v207, v203 row_shr:4 row_mask:0xf bank_mask:0xa
	v_max_f32_e64 v105, |v17|, |v104|
	v_max_f32_e64 v106, |v103|, |v16|
	v_max3_f32 v98, v98, v105, v106
	v_lshlrev_b32_e32 v105, 16, v14
	v_and_b32_e32 v14, 0xffff0000, v14
	v_lshlrev_b32_e32 v106, 16, v15
	v_and_b32_e32 v15, 0xffff0000, v15
	v_add_f32_e32 v107, v105, v14
	v_sub_f32_e32 v14, v105, v14
	v_add_f32_e32 v105, v106, v15
	v_sub_f32_e32 v15, v106, v15
	v_add_f32_e32 v106, v107, v105
	v_sub_f32_e32 v105, v107, v105
	v_add_f32_e32 v108, v14, v15
	v_sub_f32_e32 v14, v14, v15
	v_xor_b32_e32 v15, v82, v106
	v_xor_b32_e32 v107, v82, v105
	s_nop 0
	v_add_f32_dpp v15, v106, v15 quad_perm:[1,0,3,2] row_mask:0xf bank_mask:0xf bound_ctrl:1
	v_xor_b32_e32 v106, v82, v108
	v_add_f32_dpp v105, v105, v107 quad_perm:[1,0,3,2] row_mask:0xf bank_mask:0xf bound_ctrl:1
	v_xor_b32_e32 v107, v82, v14
	v_add_f32_dpp v106, v108, v106 quad_perm:[1,0,3,2] row_mask:0xf bank_mask:0xf bound_ctrl:1
	s_nop 0
	v_add_f32_dpp v14, v14, v107 quad_perm:[1,0,3,2] row_mask:0xf bank_mask:0xf bound_ctrl:1
	v_xor_b32_e32 v200, v83, v15
	v_xor_b32_e32 v201, v83, v106
	v_xor_b32_e32 v202, v83, v105
	v_xor_b32_e32 v203, v83, v14
	v_add_f32_dpp v204, v15, v200 quad_perm:[2,3,0,1] row_mask:0xf bank_mask:0xf bound_ctrl:1
	v_add_f32_dpp v205, v106, v201 quad_perm:[2,3,0,1] row_mask:0xf bank_mask:0xf bound_ctrl:1
	v_add_f32_dpp v206, v105, v202 quad_perm:[2,3,0,1] row_mask:0xf bank_mask:0xf bound_ctrl:1
	v_add_f32_dpp v207, v14, v203 quad_perm:[2,3,0,1] row_mask:0xf bank_mask:0xf bound_ctrl:1
	v_xor_b32_e32 v200, v84, v204
	v_xor_b32_e32 v201, v84, v205
	v_xor_b32_e32 v202, v84, v206
	v_xor_b32_e32 v203, v84, v207
	v_add_f32_dpp v15, v204, v200 row_shl:4 row_mask:0xf bank_mask:0x5
	v_add_f32_dpp v106, v205, v201 row_shl:4 row_mask:0xf bank_mask:0x5
	v_add_f32_dpp v105, v206, v202 row_shl:4 row_mask:0xf bank_mask:0x5
	v_add_f32_dpp v14, v207, v203 row_shl:4 row_mask:0xf bank_mask:0x5
	v_add_f32_dpp v15, v204, v200 row_shr:4 row_mask:0xf bank_mask:0xa
	v_add_f32_dpp v106, v205, v201 row_shr:4 row_mask:0xf bank_mask:0xa
	v_add_f32_dpp v105, v206, v202 row_shr:4 row_mask:0xf bank_mask:0xa
	v_add_f32_dpp v14, v207, v203 row_shr:4 row_mask:0xf bank_mask:0xa
	v_max_f32_e64 v107, |v15|, |v106|
	v_max_f32_e64 v108, |v105|, |v14|
	v_max3_f32 v98, v98, v107, v108
	v_lshlrev_b32_e32 v107, 16, v12
	v_and_b32_e32 v12, 0xffff0000, v12
	v_lshlrev_b32_e32 v108, 16, v13
	v_and_b32_e32 v13, 0xffff0000, v13
	v_add_f32_e32 v109, v107, v12
	v_sub_f32_e32 v12, v107, v12
	v_add_f32_e32 v107, v108, v13
	v_sub_f32_e32 v13, v108, v13
	v_add_f32_e32 v108, v109, v107
	v_sub_f32_e32 v107, v109, v107
	v_add_f32_e32 v110, v12, v13
	v_sub_f32_e32 v12, v12, v13
	v_xor_b32_e32 v13, v82, v108
	v_xor_b32_e32 v109, v82, v107
	s_nop 0
	v_add_f32_dpp v13, v108, v13 quad_perm:[1,0,3,2] row_mask:0xf bank_mask:0xf bound_ctrl:1
	v_xor_b32_e32 v108, v82, v110
	v_add_f32_dpp v107, v107, v109 quad_perm:[1,0,3,2] row_mask:0xf bank_mask:0xf bound_ctrl:1
	v_xor_b32_e32 v109, v82, v12
	v_add_f32_dpp v108, v110, v108 quad_perm:[1,0,3,2] row_mask:0xf bank_mask:0xf bound_ctrl:1
	s_nop 0
	v_add_f32_dpp v12, v12, v109 quad_perm:[1,0,3,2] row_mask:0xf bank_mask:0xf bound_ctrl:1
	v_xor_b32_e32 v200, v83, v13
	v_xor_b32_e32 v201, v83, v108
	v_xor_b32_e32 v202, v83, v107
	v_xor_b32_e32 v203, v83, v12
	v_add_f32_dpp v204, v13, v200 quad_perm:[2,3,0,1] row_mask:0xf bank_mask:0xf bound_ctrl:1
	v_add_f32_dpp v205, v108, v201 quad_perm:[2,3,0,1] row_mask:0xf bank_mask:0xf bound_ctrl:1
	v_add_f32_dpp v206, v107, v202 quad_perm:[2,3,0,1] row_mask:0xf bank_mask:0xf bound_ctrl:1
	v_add_f32_dpp v207, v12, v203 quad_perm:[2,3,0,1] row_mask:0xf bank_mask:0xf bound_ctrl:1
	v_xor_b32_e32 v200, v84, v204
	v_xor_b32_e32 v201, v84, v205
	v_xor_b32_e32 v202, v84, v206
	v_xor_b32_e32 v203, v84, v207
	v_add_f32_dpp v13, v204, v200 row_shl:4 row_mask:0xf bank_mask:0x5
	v_add_f32_dpp v108, v205, v201 row_shl:4 row_mask:0xf bank_mask:0x5
	v_add_f32_dpp v107, v206, v202 row_shl:4 row_mask:0xf bank_mask:0x5
	v_add_f32_dpp v12, v207, v203 row_shl:4 row_mask:0xf bank_mask:0x5
	v_add_f32_dpp v13, v204, v200 row_shr:4 row_mask:0xf bank_mask:0xa
	v_add_f32_dpp v108, v205, v201 row_shr:4 row_mask:0xf bank_mask:0xa
	v_add_f32_dpp v107, v206, v202 row_shr:4 row_mask:0xf bank_mask:0xa
	v_add_f32_dpp v12, v207, v203 row_shr:4 row_mask:0xf bank_mask:0xa
	v_max_f32_e64 v109, |v13|, |v108|
	v_max_f32_e64 v110, |v107|, |v12|
	v_max3_f32 v98, v98, v109, v110
	v_lshlrev_b32_e32 v109, 16, v10
	v_and_b32_e32 v10, 0xffff0000, v10
	v_lshlrev_b32_e32 v110, 16, v11
	v_and_b32_e32 v11, 0xffff0000, v11
	v_add_f32_e32 v111, v109, v10
	v_sub_f32_e32 v10, v109, v10
	v_add_f32_e32 v109, v110, v11
	v_sub_f32_e32 v11, v110, v11
	v_add_f32_e32 v110, v111, v109
	v_sub_f32_e32 v109, v111, v109
	v_add_f32_e32 v112, v10, v11
	v_sub_f32_e32 v10, v10, v11
	v_xor_b32_e32 v11, v82, v110
	v_xor_b32_e32 v111, v82, v109
	s_nop 0
	v_add_f32_dpp v11, v110, v11 quad_perm:[1,0,3,2] row_mask:0xf bank_mask:0xf bound_ctrl:1
	v_xor_b32_e32 v110, v82, v112
	v_add_f32_dpp v109, v109, v111 quad_perm:[1,0,3,2] row_mask:0xf bank_mask:0xf bound_ctrl:1
	v_xor_b32_e32 v111, v82, v10
	v_add_f32_dpp v110, v112, v110 quad_perm:[1,0,3,2] row_mask:0xf bank_mask:0xf bound_ctrl:1
	s_nop 0
	v_add_f32_dpp v10, v10, v111 quad_perm:[1,0,3,2] row_mask:0xf bank_mask:0xf bound_ctrl:1
	v_xor_b32_e32 v200, v83, v11
	v_xor_b32_e32 v201, v83, v110
	v_xor_b32_e32 v202, v83, v109
	v_xor_b32_e32 v203, v83, v10
	v_add_f32_dpp v204, v11, v200 quad_perm:[2,3,0,1] row_mask:0xf bank_mask:0xf bound_ctrl:1
	v_add_f32_dpp v205, v110, v201 quad_perm:[2,3,0,1] row_mask:0xf bank_mask:0xf bound_ctrl:1
	v_add_f32_dpp v206, v109, v202 quad_perm:[2,3,0,1] row_mask:0xf bank_mask:0xf bound_ctrl:1
	v_add_f32_dpp v207, v10, v203 quad_perm:[2,3,0,1] row_mask:0xf bank_mask:0xf bound_ctrl:1
	v_xor_b32_e32 v200, v84, v204
	v_xor_b32_e32 v201, v84, v205
	v_xor_b32_e32 v202, v84, v206
	v_xor_b32_e32 v203, v84, v207
	v_add_f32_dpp v11, v204, v200 row_shl:4 row_mask:0xf bank_mask:0x5
	v_add_f32_dpp v110, v205, v201 row_shl:4 row_mask:0xf bank_mask:0x5
	v_add_f32_dpp v109, v206, v202 row_shl:4 row_mask:0xf bank_mask:0x5
	v_add_f32_dpp v10, v207, v203 row_shl:4 row_mask:0xf bank_mask:0x5
	v_add_f32_dpp v11, v204, v200 row_shr:4 row_mask:0xf bank_mask:0xa
	v_add_f32_dpp v110, v205, v201 row_shr:4 row_mask:0xf bank_mask:0xa
	v_add_f32_dpp v109, v206, v202 row_shr:4 row_mask:0xf bank_mask:0xa
	v_add_f32_dpp v10, v207, v203 row_shr:4 row_mask:0xf bank_mask:0xa
	v_max_f32_e64 v111, |v11|, |v110|
	v_max_f32_e64 v112, |v109|, |v10|
	v_max3_f32 v98, v98, v111, v112
	v_lshlrev_b32_e32 v111, 16, v8
	v_and_b32_e32 v8, 0xffff0000, v8
	v_lshlrev_b32_e32 v112, 16, v9
	v_and_b32_e32 v9, 0xffff0000, v9
	v_add_f32_e32 v113, v111, v8
	v_sub_f32_e32 v8, v111, v8
	v_add_f32_e32 v111, v112, v9
	v_sub_f32_e32 v9, v112, v9
	v_add_f32_e32 v112, v113, v111
	v_sub_f32_e32 v111, v113, v111
	v_add_f32_e32 v114, v8, v9
	v_sub_f32_e32 v8, v8, v9
	v_xor_b32_e32 v9, v82, v112
	v_xor_b32_e32 v113, v82, v111
	s_nop 0
	v_add_f32_dpp v9, v112, v9 quad_perm:[1,0,3,2] row_mask:0xf bank_mask:0xf bound_ctrl:1
	v_xor_b32_e32 v112, v82, v114
	v_add_f32_dpp v111, v111, v113 quad_perm:[1,0,3,2] row_mask:0xf bank_mask:0xf bound_ctrl:1
	v_xor_b32_e32 v113, v82, v8
	v_add_f32_dpp v112, v114, v112 quad_perm:[1,0,3,2] row_mask:0xf bank_mask:0xf bound_ctrl:1
	s_nop 0
	v_add_f32_dpp v8, v8, v113 quad_perm:[1,0,3,2] row_mask:0xf bank_mask:0xf bound_ctrl:1
	v_xor_b32_e32 v200, v83, v9
	v_xor_b32_e32 v201, v83, v112
	v_xor_b32_e32 v202, v83, v111
	v_xor_b32_e32 v203, v83, v8
	v_add_f32_dpp v204, v9, v200 quad_perm:[2,3,0,1] row_mask:0xf bank_mask:0xf bound_ctrl:1
	v_add_f32_dpp v205, v112, v201 quad_perm:[2,3,0,1] row_mask:0xf bank_mask:0xf bound_ctrl:1
	v_add_f32_dpp v206, v111, v202 quad_perm:[2,3,0,1] row_mask:0xf bank_mask:0xf bound_ctrl:1
	v_add_f32_dpp v207, v8, v203 quad_perm:[2,3,0,1] row_mask:0xf bank_mask:0xf bound_ctrl:1
	v_xor_b32_e32 v200, v84, v204
	v_xor_b32_e32 v201, v84, v205
	v_xor_b32_e32 v202, v84, v206
	v_xor_b32_e32 v203, v84, v207
	v_add_f32_dpp v9, v204, v200 row_shl:4 row_mask:0xf bank_mask:0x5
	v_add_f32_dpp v112, v205, v201 row_shl:4 row_mask:0xf bank_mask:0x5
	v_add_f32_dpp v111, v206, v202 row_shl:4 row_mask:0xf bank_mask:0x5
	v_add_f32_dpp v8, v207, v203 row_shl:4 row_mask:0xf bank_mask:0x5
	v_add_f32_dpp v9, v204, v200 row_shr:4 row_mask:0xf bank_mask:0xa
	v_add_f32_dpp v112, v205, v201 row_shr:4 row_mask:0xf bank_mask:0xa
	v_add_f32_dpp v111, v206, v202 row_shr:4 row_mask:0xf bank_mask:0xa
	v_add_f32_dpp v8, v207, v203 row_shr:4 row_mask:0xf bank_mask:0xa
	v_max_f32_e64 v113, |v9|, |v112|
	v_max_f32_e64 v114, |v111|, |v8|
	v_max3_f32 v98, v98, v113, v114
	v_lshlrev_b32_e32 v113, 16, v6
	v_and_b32_e32 v6, 0xffff0000, v6
	v_lshlrev_b32_e32 v114, 16, v7
	v_and_b32_e32 v7, 0xffff0000, v7
	v_add_f32_e32 v115, v113, v6
	v_sub_f32_e32 v6, v113, v6
	v_add_f32_e32 v113, v114, v7
	v_sub_f32_e32 v7, v114, v7
	v_add_f32_e32 v114, v115, v113
	v_sub_f32_e32 v113, v115, v113
	v_add_f32_e32 v116, v6, v7
	v_sub_f32_e32 v6, v6, v7
	v_xor_b32_e32 v7, v82, v114
	v_xor_b32_e32 v115, v82, v113
	s_nop 0
	v_add_f32_dpp v7, v114, v7 quad_perm:[1,0,3,2] row_mask:0xf bank_mask:0xf bound_ctrl:1
	v_xor_b32_e32 v114, v82, v116
	v_add_f32_dpp v113, v113, v115 quad_perm:[1,0,3,2] row_mask:0xf bank_mask:0xf bound_ctrl:1
	v_xor_b32_e32 v115, v82, v6
	v_add_f32_dpp v114, v116, v114 quad_perm:[1,0,3,2] row_mask:0xf bank_mask:0xf bound_ctrl:1
	s_nop 0
	v_add_f32_dpp v6, v6, v115 quad_perm:[1,0,3,2] row_mask:0xf bank_mask:0xf bound_ctrl:1
	v_xor_b32_e32 v200, v83, v7
	v_xor_b32_e32 v201, v83, v114
	v_xor_b32_e32 v202, v83, v113
	v_xor_b32_e32 v203, v83, v6
	v_add_f32_dpp v204, v7, v200 quad_perm:[2,3,0,1] row_mask:0xf bank_mask:0xf bound_ctrl:1
	v_add_f32_dpp v205, v114, v201 quad_perm:[2,3,0,1] row_mask:0xf bank_mask:0xf bound_ctrl:1
	v_add_f32_dpp v206, v113, v202 quad_perm:[2,3,0,1] row_mask:0xf bank_mask:0xf bound_ctrl:1
	v_add_f32_dpp v207, v6, v203 quad_perm:[2,3,0,1] row_mask:0xf bank_mask:0xf bound_ctrl:1
	v_xor_b32_e32 v200, v84, v204
	v_xor_b32_e32 v201, v84, v205
	v_xor_b32_e32 v202, v84, v206
	v_xor_b32_e32 v203, v84, v207
	v_add_f32_dpp v7, v204, v200 row_shl:4 row_mask:0xf bank_mask:0x5
	v_add_f32_dpp v114, v205, v201 row_shl:4 row_mask:0xf bank_mask:0x5
	v_add_f32_dpp v113, v206, v202 row_shl:4 row_mask:0xf bank_mask:0x5
	v_add_f32_dpp v6, v207, v203 row_shl:4 row_mask:0xf bank_mask:0x5
	v_add_f32_dpp v7, v204, v200 row_shr:4 row_mask:0xf bank_mask:0xa
	v_add_f32_dpp v114, v205, v201 row_shr:4 row_mask:0xf bank_mask:0xa
	v_add_f32_dpp v113, v206, v202 row_shr:4 row_mask:0xf bank_mask:0xa
	v_add_f32_dpp v6, v207, v203 row_shr:4 row_mask:0xf bank_mask:0xa
	v_max_f32_e64 v115, |v7|, |v114|
	v_max_f32_e64 v116, |v113|, |v6|
	v_max3_f32 v98, v98, v115, v116
	s_waitcnt vmcnt(0)
	v_lshlrev_b32_e32 v115, 16, v4
	v_and_b32_e32 v4, 0xffff0000, v4
	v_lshlrev_b32_e32 v116, 16, v5
	v_and_b32_e32 v5, 0xffff0000, v5
	v_add_f32_e32 v117, v115, v4
	v_sub_f32_e32 v4, v115, v4
	v_add_f32_e32 v115, v116, v5
	v_sub_f32_e32 v5, v116, v5
	v_add_f32_e32 v116, v117, v115
	v_sub_f32_e32 v115, v117, v115
	v_add_f32_e32 v118, v4, v5
	v_sub_f32_e32 v4, v4, v5
	v_xor_b32_e32 v5, v82, v116
	v_xor_b32_e32 v117, v82, v115
	s_nop 0
	v_add_f32_dpp v5, v116, v5 quad_perm:[1,0,3,2] row_mask:0xf bank_mask:0xf bound_ctrl:1
	v_xor_b32_e32 v116, v82, v118
	v_add_f32_dpp v115, v115, v117 quad_perm:[1,0,3,2] row_mask:0xf bank_mask:0xf bound_ctrl:1
	v_xor_b32_e32 v117, v82, v4
	v_add_f32_dpp v116, v118, v116 quad_perm:[1,0,3,2] row_mask:0xf bank_mask:0xf bound_ctrl:1
	s_nop 0
	v_add_f32_dpp v4, v4, v117 quad_perm:[1,0,3,2] row_mask:0xf bank_mask:0xf bound_ctrl:1
	v_xor_b32_e32 v200, v83, v5
	v_xor_b32_e32 v201, v83, v116
	v_xor_b32_e32 v202, v83, v115
	v_xor_b32_e32 v203, v83, v4
	v_add_f32_dpp v204, v5, v200 quad_perm:[2,3,0,1] row_mask:0xf bank_mask:0xf bound_ctrl:1
	v_add_f32_dpp v205, v116, v201 quad_perm:[2,3,0,1] row_mask:0xf bank_mask:0xf bound_ctrl:1
	v_add_f32_dpp v206, v115, v202 quad_perm:[2,3,0,1] row_mask:0xf bank_mask:0xf bound_ctrl:1
	v_add_f32_dpp v207, v4, v203 quad_perm:[2,3,0,1] row_mask:0xf bank_mask:0xf bound_ctrl:1
	v_xor_b32_e32 v200, v84, v204
	v_xor_b32_e32 v201, v84, v205
	v_xor_b32_e32 v202, v84, v206
	v_xor_b32_e32 v203, v84, v207
	v_add_f32_dpp v5, v204, v200 row_shl:4 row_mask:0xf bank_mask:0x5
	v_add_f32_dpp v116, v205, v201 row_shl:4 row_mask:0xf bank_mask:0x5
	v_add_f32_dpp v115, v206, v202 row_shl:4 row_mask:0xf bank_mask:0x5
	v_add_f32_dpp v4, v207, v203 row_shl:4 row_mask:0xf bank_mask:0x5
	v_add_f32_dpp v5, v204, v200 row_shr:4 row_mask:0xf bank_mask:0xa
	v_add_f32_dpp v116, v205, v201 row_shr:4 row_mask:0xf bank_mask:0xa
	v_add_f32_dpp v115, v206, v202 row_shr:4 row_mask:0xf bank_mask:0xa
	v_add_f32_dpp v4, v207, v203 row_shr:4 row_mask:0xf bank_mask:0xa
	v_max_f32_e64 v117, |v5|, |v116|
	v_max_f32_e64 v118, |v115|, |v4|
	v_max3_f32 v98, v98, v117, v118
	ds_swizzle_b32 v117, v98 offset:swizzle(SWAP,1)
	s_waitcnt lgkmcnt(0)
	v_max_f32_e32 v94, v117, v117
	v_max_f32_e32 v94, v98, v94
	ds_swizzle_b32 v95, v94 offset:swizzle(SWAP,2)
	v_cvt_pk_bf16_f32 v98, v101, v18
	s_waitcnt lgkmcnt(0)
	v_max_f32_e32 v18, v95, v95
	v_max_f32_e32 v18, v94, v18
	ds_swizzle_b32 v20, v18 offset:swizzle(SWAP,4)
	v_cvt_pk_bf16_f32 v94, v17, v104
	v_cvt_pk_bf16_f32 v95, v103, v16
	v_cvt_pk_bf16_f32 v99, v15, v106
	v_cvt_pk_bf16_f32 v100, v105, v14
	s_waitcnt lgkmcnt(0)
	v_max_f32_e32 v14, v20, v20
	v_max_f32_e32 v14, v18, v14
	ds_swizzle_b32 v16, v14 offset:swizzle(SWAP,8)
	v_cvt_pk_bf16_f32 v18, v13, v108
	v_cvt_pk_bf16_f32 v101, v107, v12
	v_cvt_pk_bf16_f32 v15, v11, v110
	v_cvt_pk_bf16_f32 v17, v109, v10
	s_waitcnt lgkmcnt(0)
	v_max_f32_e32 v10, v16, v16
	v_max_f32_e32 v10, v14, v10
	ds_swizzle_b32 v12, v10 offset:swizzle(SWAP,16)
	v_cvt_pk_bf16_f32 v13, v9, v112
	v_cvt_pk_bf16_f32 v14, v111, v8
	v_cvt_pk_bf16_f32 v9, v7, v114
	v_cvt_pk_bf16_f32 v11, v113, v6
	s_waitcnt lgkmcnt(0)
	v_max_f32_e32 v6, v12, v12
	v_max_f32_e32 v6, v10, v6
	v_mov_b32_e32 v7, v6
	s_nop 1
	v_permlane32_swap_b32_e32 v6, v7
	v_max_f32_e32 v7, v7, v7
	v_max_f32_e32 v6, v6, v6
	v_max_f32_e32 v6, v6, v7
	v_mul_f32_e32 v8, 0x3f808000, v6
	v_div_scale_f32 v6, s[18:19], v8, v8, s27
	v_rcp_f32_e32 v7, v6
	v_cvt_pk_bf16_f32 v10, v5, v116
	v_cvt_pk_bf16_f32 v12, v115, v4
	v_lshl_add_u64 v[4:5], s[8:9], 0, v[0:1]
	v_fma_f32 v16, -v6, v7, 1.0
	v_fmac_f32_e32 v7, v16, v7
	v_div_scale_f32 v16, vcc, s27, v8, s27
	v_mul_f32_e32 v20, v16, v7
	v_fma_f32 v21, -v6, v20, v16
	v_fmac_f32_e32 v20, v21, v7
	v_fma_f32 v6, -v6, v20, v16
	v_div_fmas_f32 v6, v6, v7, v20
	v_div_fixup_f32 v6, v6, v8, s27
	v_cmp_lt_f32_e32 vcc, 0, v8
	v_lshlrev_b32_e32 v7, 16, v87
	v_lshlrev_b32_e32 v20, 16, v86
	v_cndmask_b32_e32 v16, 0, v6, vcc
	v_and_b32_e32 v6, 0xffff0000, v87
	v_fmaak_f32 v6, v6, v16, 0x4b400000
	v_fmaak_f32 v7, v7, v16, 0x4b400000
	v_perm_b32 v6, v6, v7, s28
	v_and_b32_e32 v7, 0xffff0000, v86
	v_fmaak_f32 v7, v7, v16, 0x4b400000
	v_fmaak_f32 v20, v20, v16, 0x4b400000
	v_perm_b32 v7, v7, v20, s28
	v_add_co_u32_e32 v20, vcc, s30, v4
	v_perm_b32 v86, v6, v7, s29
	s_nop 0
	v_addc_co_u32_e32 v21, vcc, 0, v5, vcc
	v_add_co_u32_e32 v6, vcc, s31, v4
	v_lshlrev_b32_e32 v87, 16, v89
	s_nop 0
	v_addc_co_u32_e32 v7, vcc, 0, v5, vcc
	global_store_dword v[6:7], v86, off offset:-4096 nt
	v_and_b32_e32 v86, 0xffff0000, v89
	v_fmaak_f32 v86, v86, v16, 0x4b400000
	v_fmaak_f32 v87, v87, v16, 0x4b400000
	v_perm_b32 v86, v86, v87, s28
	v_and_b32_e32 v87, 0xffff0000, v88
	v_lshlrev_b32_e32 v88, 16, v88
	v_fmaak_f32 v87, v87, v16, 0x4b400000
	v_fmaak_f32 v88, v88, v16, 0x4b400000
	v_perm_b32 v87, v87, v88, s28
	v_perm_b32 v86, v86, v87, s29
	global_store_dword v[20:21], v86, off offset:256 nt
	v_and_b32_e32 v86, 0xffff0000, v91
	v_lshlrev_b32_e32 v87, 16, v91
	v_fmaak_f32 v86, v86, v16, 0x4b400000
	v_fmaak_f32 v87, v87, v16, 0x4b400000
	v_perm_b32 v86, v86, v87, s28
	v_and_b32_e32 v87, 0xffff0000, v90
	v_lshlrev_b32_e32 v88, 16, v90
	v_fmaak_f32 v87, v87, v16, 0x4b400000
	v_fmaak_f32 v88, v88, v16, 0x4b400000
	v_perm_b32 v87, v87, v88, s28
	v_perm_b32 v86, v86, v87, s29
	global_store_dword v[20:21], v86, off offset:512 nt
	v_and_b32_e32 v86, 0xffff0000, v93
	v_lshlrev_b32_e32 v87, 16, v93
	v_fmaak_f32 v86, v86, v16, 0x4b400000
	v_fmaak_f32 v87, v87, v16, 0x4b400000
	v_perm_b32 v86, v86, v87, s28
	v_and_b32_e32 v87, 0xffff0000, v92
	v_lshlrev_b32_e32 v88, 16, v92
	v_fmaak_f32 v87, v87, v16, 0x4b400000
	v_fmaak_f32 v88, v88, v16, 0x4b400000
	v_perm_b32 v87, v87, v88, s28
	v_perm_b32 v86, v86, v87, s29
	global_store_dword v[20:21], v86, off offset:768 nt
	v_and_b32_e32 v86, 0xffff0000, v81
	v_lshlrev_b32_e32 v81, 16, v81
	v_fmaak_f32 v86, v86, v16, 0x4b400000
	v_fmaak_f32 v81, v81, v16, 0x4b400000
	v_perm_b32 v81, v86, v81, s28
	v_and_b32_e32 v86, 0xffff0000, v80
	v_lshlrev_b32_e32 v80, 16, v80
	v_fmaak_f32 v86, v86, v16, 0x4b400000
	v_fmaak_f32 v80, v80, v16, 0x4b400000
	v_perm_b32 v80, v86, v80, s28
	v_perm_b32 v80, v81, v80, s29
	global_store_dword v[20:21], v80, off offset:1024 nt
	v_and_b32_e32 v80, 0xffff0000, v79
	v_lshlrev_b32_e32 v79, 16, v79
	v_fmaak_f32 v80, v80, v16, 0x4b400000
	v_fmaak_f32 v79, v79, v16, 0x4b400000
	v_perm_b32 v79, v80, v79, s28
	v_and_b32_e32 v80, 0xffff0000, v78
	v_lshlrev_b32_e32 v78, 16, v78
	v_fmaak_f32 v80, v80, v16, 0x4b400000
	v_fmaak_f32 v78, v78, v16, 0x4b400000
	v_perm_b32 v78, v80, v78, s28
	v_perm_b32 v78, v79, v78, s29
	global_store_dword v[20:21], v78, off offset:1280 nt
	v_and_b32_e32 v78, 0xffff0000, v77
	v_lshlrev_b32_e32 v77, 16, v77
	v_fmaak_f32 v78, v78, v16, 0x4b400000
	v_fmaak_f32 v77, v77, v16, 0x4b400000
	v_perm_b32 v77, v78, v77, s28
	v_and_b32_e32 v78, 0xffff0000, v76
	v_lshlrev_b32_e32 v76, 16, v76
	v_fmaak_f32 v78, v78, v16, 0x4b400000
	v_fmaak_f32 v76, v76, v16, 0x4b400000
	v_perm_b32 v76, v78, v76, s28
	v_perm_b32 v76, v77, v76, s29
	global_store_dword v[20:21], v76, off offset:1536 nt
	v_and_b32_e32 v76, 0xffff0000, v75
	v_lshlrev_b32_e32 v75, 16, v75
	v_fmaak_f32 v76, v76, v16, 0x4b400000
	v_fmaak_f32 v75, v75, v16, 0x4b400000
	v_perm_b32 v75, v76, v75, s28
	v_and_b32_e32 v76, 0xffff0000, v74
	v_lshlrev_b32_e32 v74, 16, v74
	v_fmaak_f32 v76, v76, v16, 0x4b400000
	v_fmaak_f32 v74, v74, v16, 0x4b400000
	v_perm_b32 v74, v76, v74, s28
	v_perm_b32 v74, v75, v74, s29
	global_store_dword v[20:21], v74, off offset:1792 nt
	v_and_b32_e32 v74, 0xffff0000, v73
	v_lshlrev_b32_e32 v73, 16, v73
	v_fmaak_f32 v74, v74, v16, 0x4b400000
	v_fmaak_f32 v73, v73, v16, 0x4b400000
	v_perm_b32 v73, v74, v73, s28
	v_and_b32_e32 v74, 0xffff0000, v72
	v_lshlrev_b32_e32 v72, 16, v72
	v_fmaak_f32 v74, v74, v16, 0x4b400000
	v_fmaak_f32 v72, v72, v16, 0x4b400000
	v_perm_b32 v72, v74, v72, s28
	v_perm_b32 v72, v73, v72, s29
	global_store_dword v[20:21], v72, off offset:2048 nt
	v_and_b32_e32 v72, 0xffff0000, v71
	v_lshlrev_b32_e32 v71, 16, v71
	v_fmaak_f32 v72, v72, v16, 0x4b400000
	v_fmaak_f32 v71, v71, v16, 0x4b400000
	v_perm_b32 v71, v72, v71, s28
	v_and_b32_e32 v72, 0xffff0000, v70
	v_lshlrev_b32_e32 v70, 16, v70
	v_fmaak_f32 v72, v72, v16, 0x4b400000
	v_fmaak_f32 v70, v70, v16, 0x4b400000
	v_perm_b32 v70, v72, v70, s28
	v_perm_b32 v70, v71, v70, s29
	global_store_dword v[20:21], v70, off offset:2304 nt
	v_and_b32_e32 v70, 0xffff0000, v69
	v_lshlrev_b32_e32 v69, 16, v69
	v_fmaak_f32 v70, v70, v16, 0x4b400000
	v_fmaak_f32 v69, v69, v16, 0x4b400000
	v_perm_b32 v69, v70, v69, s28
	v_and_b32_e32 v70, 0xffff0000, v68
	v_lshlrev_b32_e32 v68, 16, v68
	v_fmaak_f32 v70, v70, v16, 0x4b400000
	v_fmaak_f32 v68, v68, v16, 0x4b400000
	v_perm_b32 v68, v70, v68, s28
	v_perm_b32 v68, v69, v68, s29
	global_store_dword v[20:21], v68, off offset:2560 nt
	v_and_b32_e32 v68, 0xffff0000, v67
	v_lshlrev_b32_e32 v67, 16, v67
	v_fmaak_f32 v68, v68, v16, 0x4b400000
	v_fmaak_f32 v67, v67, v16, 0x4b400000
	v_perm_b32 v67, v68, v67, s28
	v_and_b32_e32 v68, 0xffff0000, v66
	v_lshlrev_b32_e32 v66, 16, v66
	v_fmaak_f32 v68, v68, v16, 0x4b400000
	v_fmaak_f32 v66, v66, v16, 0x4b400000
	v_perm_b32 v66, v68, v66, s28
	v_perm_b32 v66, v67, v66, s29
	global_store_dword v[20:21], v66, off offset:2816 nt
	v_and_b32_e32 v66, 0xffff0000, v65
	v_lshlrev_b32_e32 v65, 16, v65
	v_fmaak_f32 v66, v66, v16, 0x4b400000
	v_fmaak_f32 v65, v65, v16, 0x4b400000
	v_perm_b32 v65, v66, v65, s28
	v_and_b32_e32 v66, 0xffff0000, v64
	v_lshlrev_b32_e32 v64, 16, v64
	v_fmaak_f32 v66, v66, v16, 0x4b400000
	v_fmaak_f32 v64, v64, v16, 0x4b400000
	v_perm_b32 v64, v66, v64, s28
	v_perm_b32 v64, v65, v64, s29
	global_store_dword v[20:21], v64, off offset:3072 nt
	v_and_b32_e32 v64, 0xffff0000, v63
	v_lshlrev_b32_e32 v63, 16, v63
	v_fmaak_f32 v64, v64, v16, 0x4b400000
	v_fmaak_f32 v63, v63, v16, 0x4b400000
	v_perm_b32 v63, v64, v63, s28
	v_and_b32_e32 v64, 0xffff0000, v62
	v_lshlrev_b32_e32 v62, 16, v62
	v_fmaak_f32 v64, v64, v16, 0x4b400000
	v_fmaak_f32 v62, v62, v16, 0x4b400000
	v_perm_b32 v62, v64, v62, s28
	v_perm_b32 v62, v63, v62, s29
	global_store_dword v[20:21], v62, off offset:3328 nt
	v_and_b32_e32 v62, 0xffff0000, v61
	v_lshlrev_b32_e32 v61, 16, v61
	v_fmaak_f32 v62, v62, v16, 0x4b400000
	v_fmaak_f32 v61, v61, v16, 0x4b400000
	v_perm_b32 v61, v62, v61, s28
	v_and_b32_e32 v62, 0xffff0000, v60
	v_lshlrev_b32_e32 v60, 16, v60
	v_fmaak_f32 v62, v62, v16, 0x4b400000
	v_fmaak_f32 v60, v60, v16, 0x4b400000
	v_perm_b32 v60, v62, v60, s28
	v_perm_b32 v60, v61, v60, s29
	global_store_dword v[20:21], v60, off offset:3584 nt
	v_and_b32_e32 v60, 0xffff0000, v59
	v_lshlrev_b32_e32 v59, 16, v59
	v_fmaak_f32 v60, v60, v16, 0x4b400000
	v_fmaak_f32 v59, v59, v16, 0x4b400000
	v_perm_b32 v59, v60, v59, s28
	v_and_b32_e32 v60, 0xffff0000, v58
	v_lshlrev_b32_e32 v58, 16, v58
	v_fmaak_f32 v60, v60, v16, 0x4b400000
	v_fmaak_f32 v58, v58, v16, 0x4b400000
	v_perm_b32 v58, v60, v58, s28
	v_perm_b32 v58, v59, v58, s29
	global_store_dword v[20:21], v58, off offset:3840 nt
	v_and_b32_e32 v20, 0xffff0000, v57
	v_lshlrev_b32_e32 v21, 16, v57
	v_fmaak_f32 v20, v20, v16, 0x4b400000
	v_fmaak_f32 v21, v21, v16, 0x4b400000
	v_perm_b32 v20, v20, v21, s28
	v_and_b32_e32 v21, 0xffff0000, v56
	v_lshlrev_b32_e32 v56, 16, v56
	v_fmaak_f32 v21, v21, v16, 0x4b400000
	v_fmaak_f32 v56, v56, v16, 0x4b400000
	v_perm_b32 v21, v21, v56, s28
	v_perm_b32 v20, v20, v21, s29
	global_store_dword v[6:7], v20, off nt
	v_and_b32_e32 v20, 0xffff0000, v55
	v_lshlrev_b32_e32 v21, 16, v55
	v_fmaak_f32 v20, v20, v16, 0x4b400000
	v_fmaak_f32 v21, v21, v16, 0x4b400000
	v_perm_b32 v20, v20, v21, s28
	v_and_b32_e32 v21, 0xffff0000, v54
	v_lshlrev_b32_e32 v54, 16, v54
	v_fmaak_f32 v21, v21, v16, 0x4b400000
	v_fmaak_f32 v54, v54, v16, 0x4b400000
	v_perm_b32 v21, v21, v54, s28
	v_perm_b32 v20, v20, v21, s29
	global_store_dword v[6:7], v20, off offset:256 nt
	v_and_b32_e32 v20, 0xffff0000, v53
	v_lshlrev_b32_e32 v21, 16, v53
	v_fmaak_f32 v20, v20, v16, 0x4b400000
	v_fmaak_f32 v21, v21, v16, 0x4b400000
	v_perm_b32 v20, v20, v21, s28
	v_and_b32_e32 v21, 0xffff0000, v52
	v_lshlrev_b32_e32 v52, 16, v52
	v_fmaak_f32 v21, v21, v16, 0x4b400000
	v_fmaak_f32 v52, v52, v16, 0x4b400000
	v_perm_b32 v21, v21, v52, s28
	v_perm_b32 v20, v20, v21, s29
	global_store_dword v[6:7], v20, off offset:512 nt
	v_and_b32_e32 v20, 0xffff0000, v51
	v_lshlrev_b32_e32 v21, 16, v51
	v_fmaak_f32 v20, v20, v16, 0x4b400000
	v_fmaak_f32 v21, v21, v16, 0x4b400000
	v_perm_b32 v20, v20, v21, s28
	v_and_b32_e32 v21, 0xffff0000, v50
	v_lshlrev_b32_e32 v50, 16, v50
	v_fmaak_f32 v21, v21, v16, 0x4b400000
	v_fmaak_f32 v50, v50, v16, 0x4b400000
	v_perm_b32 v21, v21, v50, s28
	v_perm_b32 v20, v20, v21, s29
	global_store_dword v[6:7], v20, off offset:768 nt
	v_and_b32_e32 v20, 0xffff0000, v49
	v_lshlrev_b32_e32 v21, 16, v49
	v_fmaak_f32 v20, v20, v16, 0x4b400000
	v_fmaak_f32 v21, v21, v16, 0x4b400000
	v_perm_b32 v20, v20, v21, s28
	v_and_b32_e32 v21, 0xffff0000, v48
	v_lshlrev_b32_e32 v48, 16, v48
	v_fmaak_f32 v21, v21, v16, 0x4b400000
	v_fmaak_f32 v48, v48, v16, 0x4b400000
	v_perm_b32 v21, v21, v48, s28
	v_perm_b32 v20, v20, v21, s29
	global_store_dword v[6:7], v20, off offset:1024 nt
	v_and_b32_e32 v20, 0xffff0000, v47
	v_lshlrev_b32_e32 v21, 16, v47
	v_fmaak_f32 v20, v20, v16, 0x4b400000
	v_fmaak_f32 v21, v21, v16, 0x4b400000
	v_perm_b32 v20, v20, v21, s28
	v_and_b32_e32 v21, 0xffff0000, v46
	v_lshlrev_b32_e32 v46, 16, v46
	v_fmaak_f32 v21, v21, v16, 0x4b400000
	v_fmaak_f32 v46, v46, v16, 0x4b400000
	v_perm_b32 v21, v21, v46, s28
	v_perm_b32 v20, v20, v21, s29
	global_store_dword v[6:7], v20, off offset:1280 nt
	v_and_b32_e32 v20, 0xffff0000, v45
	v_lshlrev_b32_e32 v21, 16, v45
	v_fmaak_f32 v20, v20, v16, 0x4b400000
	v_fmaak_f32 v21, v21, v16, 0x4b400000
	v_perm_b32 v20, v20, v21, s28
	v_and_b32_e32 v21, 0xffff0000, v44
	v_lshlrev_b32_e32 v44, 16, v44
	v_fmaak_f32 v21, v21, v16, 0x4b400000
	v_fmaak_f32 v44, v44, v16, 0x4b400000
	v_perm_b32 v21, v21, v44, s28
	v_perm_b32 v20, v20, v21, s29
	global_store_dword v[6:7], v20, off offset:1536 nt
	v_and_b32_e32 v20, 0xffff0000, v43
	v_lshlrev_b32_e32 v21, 16, v43
	v_fmaak_f32 v20, v20, v16, 0x4b400000
	v_fmaak_f32 v21, v21, v16, 0x4b400000
	v_perm_b32 v20, v20, v21, s28
	v_and_b32_e32 v21, 0xffff0000, v42
	v_lshlrev_b32_e32 v42, 16, v42
	v_fmaak_f32 v21, v21, v16, 0x4b400000
	v_fmaak_f32 v42, v42, v16, 0x4b400000
	v_perm_b32 v21, v21, v42, s28
	v_perm_b32 v20, v20, v21, s29
	global_store_dword v[6:7], v20, off offset:1792 nt
	v_and_b32_e32 v20, 0xffff0000, v41
	v_lshlrev_b32_e32 v21, 16, v41
	v_fmaak_f32 v20, v20, v16, 0x4b400000
	v_fmaak_f32 v21, v21, v16, 0x4b400000
	v_perm_b32 v20, v20, v21, s28
	v_and_b32_e32 v21, 0xffff0000, v40
	v_lshlrev_b32_e32 v40, 16, v40
	v_fmaak_f32 v21, v21, v16, 0x4b400000
	v_fmaak_f32 v40, v40, v16, 0x4b400000
	v_perm_b32 v21, v21, v40, s28
	v_perm_b32 v20, v20, v21, s29
	global_store_dword v[6:7], v20, off offset:2048 nt
	v_and_b32_e32 v20, 0xffff0000, v39
	v_lshlrev_b32_e32 v21, 16, v39
	v_fmaak_f32 v20, v20, v16, 0x4b400000
	v_fmaak_f32 v21, v21, v16, 0x4b400000
	v_perm_b32 v20, v20, v21, s28
	v_and_b32_e32 v21, 0xffff0000, v38
	v_lshlrev_b32_e32 v38, 16, v38
	v_fmaak_f32 v21, v21, v16, 0x4b400000
	v_fmaak_f32 v38, v38, v16, 0x4b400000
	v_perm_b32 v21, v21, v38, s28
	v_perm_b32 v20, v20, v21, s29
	global_store_dword v[6:7], v20, off offset:2304 nt
	v_and_b32_e32 v20, 0xffff0000, v37
	v_lshlrev_b32_e32 v21, 16, v37
	v_fmaak_f32 v20, v20, v16, 0x4b400000
	v_fmaak_f32 v21, v21, v16, 0x4b400000
	v_perm_b32 v20, v20, v21, s28
	v_and_b32_e32 v21, 0xffff0000, v36
	v_lshlrev_b32_e32 v36, 16, v36
	v_fmaak_f32 v21, v21, v16, 0x4b400000
	v_fmaak_f32 v36, v36, v16, 0x4b400000
	v_perm_b32 v21, v21, v36, s28
	v_perm_b32 v20, v20, v21, s29
	global_store_dword v[6:7], v20, off offset:2560 nt
	v_and_b32_e32 v20, 0xffff0000, v35
	v_lshlrev_b32_e32 v21, 16, v35
	v_fmaak_f32 v20, v20, v16, 0x4b400000
	v_fmaak_f32 v21, v21, v16, 0x4b400000
	v_perm_b32 v20, v20, v21, s28
	v_and_b32_e32 v21, 0xffff0000, v34
	v_lshlrev_b32_e32 v34, 16, v34
	v_fmaak_f32 v21, v21, v16, 0x4b400000
	v_fmaak_f32 v34, v34, v16, 0x4b400000
	v_perm_b32 v21, v21, v34, s28
	v_perm_b32 v20, v20, v21, s29
	global_store_dword v[6:7], v20, off offset:2816 nt
	v_and_b32_e32 v20, 0xffff0000, v33
	v_lshlrev_b32_e32 v21, 16, v33
	v_fmaak_f32 v20, v20, v16, 0x4b400000
	v_fmaak_f32 v21, v21, v16, 0x4b400000
	v_perm_b32 v20, v20, v21, s28
	v_and_b32_e32 v21, 0xffff0000, v32
	v_lshlrev_b32_e32 v32, 16, v32
	v_fmaak_f32 v21, v21, v16, 0x4b400000
	v_fmaak_f32 v32, v32, v16, 0x4b400000
	v_perm_b32 v21, v21, v32, s28
	v_perm_b32 v20, v20, v21, s29
	global_store_dword v[6:7], v20, off offset:3072 nt
	v_and_b32_e32 v20, 0xffff0000, v31
	v_lshlrev_b32_e32 v21, 16, v31
	v_fmaak_f32 v20, v20, v16, 0x4b400000
	v_fmaak_f32 v21, v21, v16, 0x4b400000
	v_perm_b32 v20, v20, v21, s28
	v_and_b32_e32 v21, 0xffff0000, v30
	v_lshlrev_b32_e32 v30, 16, v30
	v_fmaak_f32 v21, v21, v16, 0x4b400000
	v_fmaak_f32 v30, v30, v16, 0x4b400000
	v_perm_b32 v21, v21, v30, s28
	v_perm_b32 v20, v20, v21, s29
	global_store_dword v[6:7], v20, off offset:3328 nt
	v_and_b32_e32 v20, 0xffff0000, v29
	v_lshlrev_b32_e32 v21, 16, v29
	v_fmaak_f32 v20, v20, v16, 0x4b400000
	v_fmaak_f32 v21, v21, v16, 0x4b400000
	v_perm_b32 v20, v20, v21, s28
	v_and_b32_e32 v21, 0xffff0000, v28
	v_lshlrev_b32_e32 v28, 16, v28
	v_fmaak_f32 v21, v21, v16, 0x4b400000
	v_fmaak_f32 v28, v28, v16, 0x4b400000
	v_perm_b32 v21, v21, v28, s28
	v_perm_b32 v20, v20, v21, s29
	global_store_dword v[6:7], v20, off offset:3584 nt
	v_and_b32_e32 v20, 0xffff0000, v27
	v_lshlrev_b32_e32 v21, 16, v27
	v_fmaak_f32 v20, v20, v16, 0x4b400000
	v_fmaak_f32 v21, v21, v16, 0x4b400000
	v_perm_b32 v20, v20, v21, s28
	v_and_b32_e32 v21, 0xffff0000, v26
	v_lshlrev_b32_e32 v26, 16, v26
	v_fmaak_f32 v21, v21, v16, 0x4b400000
	v_fmaak_f32 v26, v26, v16, 0x4b400000
	v_perm_b32 v21, v21, v26, s28
	v_perm_b32 v20, v20, v21, s29
	global_store_dword v[6:7], v20, off offset:3840 nt
	v_and_b32_e32 v6, 0xffff0000, v25
	v_lshlrev_b32_e32 v7, 16, v25
	v_fmaak_f32 v6, v6, v16, 0x4b400000
	v_fmaak_f32 v7, v7, v16, 0x4b400000
	v_perm_b32 v6, v6, v7, s28
	v_and_b32_e32 v7, 0xffff0000, v24
	v_lshlrev_b32_e32 v20, 16, v24
	v_fmaak_f32 v7, v7, v16, 0x4b400000
	v_fmaak_f32 v20, v20, v16, 0x4b400000
	v_perm_b32 v7, v7, v20, s28
	v_add_co_u32_e32 v4, vcc, s34, v4
	v_perm_b32 v6, v6, v7, s29
	s_nop 0
	v_addc_co_u32_e32 v5, vcc, 0, v5, vcc
	global_store_dword v[4:5], v6, off nt
	v_and_b32_e32 v6, 0xffff0000, v23
	v_lshlrev_b32_e32 v7, 16, v23
	v_fmaak_f32 v6, v6, v16, 0x4b400000
	v_fmaak_f32 v7, v7, v16, 0x4b400000
	v_perm_b32 v6, v6, v7, s28
	v_and_b32_e32 v7, 0xffff0000, v22
	v_lshlrev_b32_e32 v20, 16, v22
	v_fmaak_f32 v7, v7, v16, 0x4b400000
	v_fmaak_f32 v20, v20, v16, 0x4b400000
	v_perm_b32 v7, v7, v20, s28
	v_perm_b32 v6, v6, v7, s29
	global_store_dword v[4:5], v6, off offset:256 nt
	v_and_b32_e32 v6, 0xffff0000, v97
	v_lshlrev_b32_e32 v7, 16, v97
	v_fmaak_f32 v6, v6, v16, 0x4b400000
	v_fmaak_f32 v7, v7, v16, 0x4b400000
	v_perm_b32 v6, v6, v7, s28
	v_and_b32_e32 v7, 0xffff0000, v96
	v_lshlrev_b32_e32 v20, 16, v96
	v_fmaak_f32 v7, v7, v16, 0x4b400000
	v_fmaak_f32 v20, v20, v16, 0x4b400000
	v_perm_b32 v7, v7, v20, s28
	v_perm_b32 v6, v6, v7, s29
	global_store_dword v[4:5], v6, off offset:512 nt
	v_and_b32_e32 v6, 0xffff0000, v98
	v_lshlrev_b32_e32 v7, 16, v98
	v_fmaak_f32 v6, v6, v16, 0x4b400000
	v_fmaak_f32 v7, v7, v16, 0x4b400000
	v_perm_b32 v6, v6, v7, s28
	v_and_b32_e32 v7, 0xffff0000, v19
	v_lshlrev_b32_e32 v19, 16, v19
	v_fmaak_f32 v7, v7, v16, 0x4b400000
	v_fmaak_f32 v19, v19, v16, 0x4b400000
	v_perm_b32 v7, v7, v19, s28
	v_perm_b32 v6, v6, v7, s29
	global_store_dword v[4:5], v6, off offset:768 nt
	v_and_b32_e32 v6, 0xffff0000, v95
	v_lshlrev_b32_e32 v7, 16, v95
	v_fmaak_f32 v6, v6, v16, 0x4b400000
	v_fmaak_f32 v7, v7, v16, 0x4b400000
	v_perm_b32 v6, v6, v7, s28
	v_and_b32_e32 v7, 0xffff0000, v94
	v_lshlrev_b32_e32 v19, 16, v94
	v_fmaak_f32 v7, v7, v16, 0x4b400000
	v_fmaak_f32 v19, v19, v16, 0x4b400000
	v_perm_b32 v7, v7, v19, s28
	v_perm_b32 v6, v6, v7, s29
	global_store_dword v[4:5], v6, off offset:1024 nt
	v_and_b32_e32 v6, 0xffff0000, v100
	v_lshlrev_b32_e32 v7, 16, v100
	v_fmaak_f32 v6, v6, v16, 0x4b400000
	v_fmaak_f32 v7, v7, v16, 0x4b400000
	v_perm_b32 v6, v6, v7, s28
	v_and_b32_e32 v7, 0xffff0000, v99
	v_lshlrev_b32_e32 v19, 16, v99
	v_fmaak_f32 v7, v7, v16, 0x4b400000
	v_fmaak_f32 v19, v19, v16, 0x4b400000
	v_perm_b32 v7, v7, v19, s28
	v_perm_b32 v6, v6, v7, s29
	global_store_dword v[4:5], v6, off offset:1280 nt
	v_and_b32_e32 v6, 0xffff0000, v101
	v_lshlrev_b32_e32 v7, 16, v101
	v_fmaak_f32 v6, v6, v16, 0x4b400000
	v_fmaak_f32 v7, v7, v16, 0x4b400000
	v_perm_b32 v6, v6, v7, s28
	v_and_b32_e32 v7, 0xffff0000, v18
	v_lshlrev_b32_e32 v18, 16, v18
	v_fmaak_f32 v7, v7, v16, 0x4b400000
	v_fmaak_f32 v18, v18, v16, 0x4b400000
	v_perm_b32 v7, v7, v18, s28
	v_perm_b32 v6, v6, v7, s29
	global_store_dword v[4:5], v6, off offset:1536 nt
	v_and_b32_e32 v6, 0xffff0000, v17
	v_lshlrev_b32_e32 v7, 16, v17
	v_fmaak_f32 v6, v6, v16, 0x4b400000
	v_fmaak_f32 v7, v7, v16, 0x4b400000
	v_perm_b32 v6, v6, v7, s28
	v_and_b32_e32 v7, 0xffff0000, v15
	v_lshlrev_b32_e32 v15, 16, v15
	v_fmaak_f32 v7, v7, v16, 0x4b400000
	v_fmaak_f32 v15, v15, v16, 0x4b400000
	v_perm_b32 v7, v7, v15, s28
	v_perm_b32 v6, v6, v7, s29
	global_store_dword v[4:5], v6, off offset:1792 nt
	v_and_b32_e32 v6, 0xffff0000, v14
	v_lshlrev_b32_e32 v7, 16, v14
	v_fmaak_f32 v6, v6, v16, 0x4b400000
	v_fmaak_f32 v7, v7, v16, 0x4b400000
	v_perm_b32 v6, v6, v7, s28
	v_and_b32_e32 v7, 0xffff0000, v13
	v_lshlrev_b32_e32 v13, 16, v13
	v_fmaak_f32 v7, v7, v16, 0x4b400000
	v_fmaak_f32 v13, v13, v16, 0x4b400000
	v_perm_b32 v7, v7, v13, s28
	v_perm_b32 v6, v6, v7, s29
	global_store_dword v[4:5], v6, off offset:2048 nt
	v_and_b32_e32 v6, 0xffff0000, v11
	v_lshlrev_b32_e32 v7, 16, v11
	v_fmaak_f32 v6, v6, v16, 0x4b400000
	v_fmaak_f32 v7, v7, v16, 0x4b400000
	v_perm_b32 v6, v6, v7, s28
	v_and_b32_e32 v7, 0xffff0000, v9
	v_lshlrev_b32_e32 v9, 16, v9
	v_fmaak_f32 v7, v7, v16, 0x4b400000
	v_fmaak_f32 v9, v9, v16, 0x4b400000
	v_perm_b32 v7, v7, v9, s28
	v_perm_b32 v6, v6, v7, s29
	global_store_dword v[4:5], v6, off offset:2304 nt
	v_and_b32_e32 v6, 0xffff0000, v12
	v_lshlrev_b32_e32 v7, 16, v12
	v_fmaak_f32 v6, v6, v16, 0x4b400000
	v_fmaak_f32 v7, v7, v16, 0x4b400000
	v_perm_b32 v6, v6, v7, s28
	v_and_b32_e32 v7, 0xffff0000, v10
	v_lshlrev_b32_e32 v9, 16, v10
	v_fmaak_f32 v7, v7, v16, 0x4b400000
	v_fmaak_f32 v9, v9, v16, 0x4b400000
	v_perm_b32 v7, v7, v9, s28
	v_perm_b32 v6, v6, v7, s29
	global_store_dword v[4:5], v6, off offset:2560 nt
	s_and_saveexec_b64 s[18:19], s[6:7]
	s_cbranch_execz .LBB0_908
	s_add_u32 s36, s8, s2
	s_addc_u32 s37, s9, s3
	v_mul_f32_e32 v4, 0x3c010204, v8
	global_store_dword v85, v4, s[36:37] nt
	s_branch .LBB0_908
